# GEMM K-loops: each accumulator's two MFMAs (k=0,k=1) issued back-to-back (SrcC forwarding) instead of 8 apart
# baseline (speedup 1.0000x reference)
; #define PG8_STAGE(bufoff, gbase, voff) do { _Pragma("unroll") for (int _i = 0; _i < 2; ++_i) \
;         __builtin_amdgcn_global_load_lds((const unsigned*)((const char*)(gbase) + (voff)[_i]), (PG8_LAS unsigned*)(lds + (bufoff) + ldsw + _i * 8192), 16, 0, 0); } while (0)
; #define PG8_LDA(dst, b, h) do { _Pragma("unroll") for (int m = 0; m < 4; ++m) _Pragma("unroll") for (int k = 0; k < 2; ++k) dst[m][k] = *(const PG8_LAS bf16x8*)(lds + PG8_SA(b, h) + aoff + m * 2048 + k * 1024); } while (0)
; #define PG8_LDB(dst, b, h) do { _Pragma("unroll") for (int n = 0; n < 2; ++n) _Pragma("unroll") for (int k = 0; k < 2; ++k) dst[n][k] = *(const PG8_LAS bf16x8*)(lds + PG8_SB(b, h) + boff + n * 2048 + k * 1024); } while (0)
; #define PG8_MMA(ai, bj, At, Bt) do { __builtin_amdgcn_s_setprio(1); _Pragma("unroll") for (int m = 0; m < 4; ++m) _Pragma("unroll") for (int n = 0; n < 2; ++n) _Pragma("unroll") for (int k = 0; k < 2; ++k) \
;         acc[ai][bj][m][n] = __builtin_amdgcn_mfma_f32_16x16x32_bf16(Bt[n][k], At[m][k], acc[ai][bj][m][n], 0, 0, 0); __builtin_amdgcn_s_setprio(0); } while (0)
; #define PG8_WAIT_V(n) asm volatile("s_waitcnt vmcnt(" #n ")" ::: "memory")
; #define PG8_WAIT_L(n) asm volatile("s_waitcnt lgkmcnt(" #n ")" ::: "memory")
; template <class Epi, class Sched, bool ALIGN_EPI = false, bool SP2 = false>
; __device__ __forceinline__ void gemm_phase(PG8_LAS unsigned char* lds, const Gemm g, const Sched& S, const Epi& E) {
;     ...
;             const bool last = (t == nt - 2);
;             const char* a1 = cA + (size_t)(t + 1) * kstep;
;             const char* a2 = last ? nA : cA + (size_t)(t + 2) * kstep; const char* b2 = last ? nB : cB + (size_t)(t + 2) * kstep;
;             const char* a3 = a2 + kstep; const char* b3 = b2 + kstep;
;             if (last && has_next) S.a_ready(nxt);
;             if constexpr (SP2) {
;             PG8_LDB(B0, 0, 0); PG8_LDB(B1, 0, 1); PG8_SCHED; PG8_LDA(At, 0, 0); PG8_STAGE(PG8_SA(1, 1), a1 + hstep, voffA);
;             PG8_WAIT_V(8); PG8_WAIT_L(0); PG8_BAR; PG8_MMA(0, 0, At, B0); PG8_MMA(0, 1, At, B1); PG8_BAR; PG8_SCHED;
;             PG8_LDA(At, 0, 1); PG8_STAGE(PG8_SB(0, 0), b2, voffB); PG8_STAGE(PG8_SB(0, 1), b2 + hstep, voffB); PG8_STAGE(PG8_SA(0, 0), a2, voffA);
;             PG8_WAIT_V(8); PG8_WAIT_L(0); PG8_BAR; PG8_MMA(1, 0, At, B0); PG8_MMA(1, 1, At, B1); PG8_BAR; PG8_SCHED;
.LBB0_265:
	s_add_u32 s10, s16, 0xfff80080
	s_addc_u32 s11, s17, -1
	s_add_i32 s27, 0, 0x10000
	s_cmp_eq_u32 s23, 28
	s_cselect_b32 s51, s5, s11
	s_cselect_b32 s50, s7, s10
	s_cselect_b32 s19, s8, s22
	s_cselect_b32 s18, s9, s15
	s_add_i32 s10, 0, 0x14000
	v_add_u32_e32 v168, s27, v157
	v_add_u32_e32 v184, s10, v157
	ds_read_b128 v[152:155], v168
	ds_read_b128 v[160:163], v168 offset:1024
	ds_read_b128 v[164:167], v168 offset:2048
	ds_read_b128 v[168:171], v168 offset:3072
	ds_read_b128 v[172:175], v184
	ds_read_b128 v[176:179], v184 offset:1024
	ds_read_b128 v[180:183], v184 offset:2048
	ds_read_b128 v[184:187], v184 offset:3072
	v_lshl_add_u64 v[200:201], s[16:17], 0, v[148:149]
	s_add_i32 m0, s57, 0xc000
	ds_read_b128 v[188:191], v159
	ds_read_b128 v[192:195], v159 offset:1024
	ds_read_b128 v[196:199], v159 offset:2048
	ds_read_b128 v[216:219], v159 offset:3072
	ds_read_b128 v[220:223], v159 offset:4096
	ds_read_b128 v[224:227], v159 offset:5120
	ds_read_b128 v[228:231], v159 offset:6144
	ds_read_b128 v[232:235], v159 offset:7168
	global_load_lds_dwordx4 v[200:201], off
	v_lshl_add_u64 v[200:201], s[16:17], 0, v[150:151]
	s_add_i32 m0, s57, 0xe000
	s_nop 0
	global_load_lds_dwordx4 v[200:201], off
	s_waitcnt vmcnt(8)
	s_waitcnt lgkmcnt(0)
	s_barrier
	s_setprio 1
	s_waitcnt lgkmcnt(0)
	v_mfma_f32_16x16x32_bf16 v[126:129], v[152:155], v[188:191], v[126:129]
	v_mfma_f32_16x16x32_bf16 v[126:129], v[160:163], v[192:195], v[126:129]
	v_mfma_f32_16x16x32_bf16 v[122:125], v[164:167], v[188:191], v[122:125]
	v_mfma_f32_16x16x32_bf16 v[122:125], v[168:171], v[192:195], v[122:125]
	v_mfma_f32_16x16x32_bf16 v[110:113], v[152:155], v[196:199], v[110:113]
	v_mfma_f32_16x16x32_bf16 v[110:113], v[160:163], v[216:219], v[110:113]
	v_mfma_f32_16x16x32_bf16 v[106:109], v[164:167], v[196:199], v[106:109]
	v_mfma_f32_16x16x32_bf16 v[106:109], v[168:171], v[216:219], v[106:109]
	v_mfma_f32_16x16x32_bf16 v[94:97], v[152:155], v[220:223], v[94:97]
	v_mfma_f32_16x16x32_bf16 v[94:97], v[160:163], v[224:227], v[94:97]
	v_mfma_f32_16x16x32_bf16 v[90:93], v[164:167], v[220:223], v[90:93]
	v_mfma_f32_16x16x32_bf16 v[90:93], v[168:171], v[224:227], v[90:93]
	v_mfma_f32_16x16x32_bf16 v[78:81], v[152:155], v[228:231], v[78:81]
	v_mfma_f32_16x16x32_bf16 v[78:81], v[160:163], v[232:235], v[78:81]
	v_mfma_f32_16x16x32_bf16 v[74:77], v[164:167], v[228:231], v[74:77]
	v_mfma_f32_16x16x32_bf16 v[74:77], v[168:171], v[232:235], v[74:77]
	s_setprio 0
	s_setprio 1
	v_mfma_f32_16x16x32_bf16 v[118:121], v[172:175], v[188:191], v[118:121]
	v_mfma_f32_16x16x32_bf16 v[118:121], v[176:179], v[192:195], v[118:121]
	v_mfma_f32_16x16x32_bf16 v[114:117], v[180:183], v[188:191], v[114:117]
	v_mfma_f32_16x16x32_bf16 v[114:117], v[184:187], v[192:195], v[114:117]
	v_mfma_f32_16x16x32_bf16 v[102:105], v[172:175], v[196:199], v[102:105]
	v_mfma_f32_16x16x32_bf16 v[102:105], v[176:179], v[216:219], v[102:105]
	v_mfma_f32_16x16x32_bf16 v[98:101], v[180:183], v[196:199], v[98:101]
	v_mfma_f32_16x16x32_bf16 v[98:101], v[184:187], v[216:219], v[98:101]
	v_mfma_f32_16x16x32_bf16 v[86:89], v[172:175], v[220:223], v[86:89]
	v_mfma_f32_16x16x32_bf16 v[86:89], v[176:179], v[224:227], v[86:89]
	v_mfma_f32_16x16x32_bf16 v[82:85], v[180:183], v[220:223], v[82:85]
	v_mfma_f32_16x16x32_bf16 v[82:85], v[184:187], v[224:227], v[82:85]
	v_mfma_f32_16x16x32_bf16 v[70:73], v[172:175], v[228:231], v[70:73]
	v_mfma_f32_16x16x32_bf16 v[70:73], v[176:179], v[232:235], v[70:73]
	v_mfma_f32_16x16x32_bf16 v[66:69], v[180:183], v[228:231], v[66:69]
	v_mfma_f32_16x16x32_bf16 v[66:69], v[184:187], v[232:235], v[66:69]
	s_setprio 0
	s_barrier
	s_add_i32 s11, s27, s56
	v_lshl_add_u64 v[200:201], s[18:19], 0, v[0:1]
	s_mov_b32 m0, s11
	ds_read_b128 v[188:191], v159 offset:16384
	ds_read_b128 v[192:195], v159 offset:17408
	ds_read_b128 v[196:199], v159 offset:18432
	ds_read_b128 v[216:219], v159 offset:19456
	ds_read_b128 v[220:223], v159 offset:20480
	ds_read_b128 v[224:227], v159 offset:21504
	ds_read_b128 v[228:231], v159 offset:22528
	ds_read_b128 v[232:235], v159 offset:23552
	global_load_lds_dwordx4 v[200:201], off
	s_add_i32 m0, s11, 0x2000
	s_add_u32 s38, s18, 0x80000
	v_lshl_add_u64 v[236:237], s[18:19], 0, v[142:143]
	s_addc_u32 s39, s19, 0
	s_add_i32 s10, s10, s56
	global_load_lds_dwordx4 v[236:237], off
	v_lshl_add_u64 v[238:239], s[38:39], 0, v[0:1]
	s_mov_b32 m0, s10
	v_lshl_add_u64 v[240:241], s[50:51], 0, v[144:145]
	global_load_lds_dwordx4 v[238:239], off
	v_lshl_add_u64 v[238:239], s[38:39], 0, v[142:143]
	s_add_i32 m0, s10, 0x2000
	s_nop 0
	global_load_lds_dwordx4 v[238:239], off
	v_lshl_add_u64 v[238:239], s[50:51], 0, v[146:147]
	s_mov_b32 m0, s57
	s_nop 0
	global_load_lds_dwordx4 v[238:239], off
	s_mov_b32 m0, s58
	s_nop 0
	global_load_lds_dwordx4 v[240:241], off
	s_waitcnt vmcnt(8)
	s_waitcnt lgkmcnt(0)
	s_barrier
; #define PG8_STAGE(bufoff, gbase, voff) do { _Pragma("unroll") for (int _i = 0; _i < 2; ++_i) \
;         __builtin_amdgcn_global_load_lds((const unsigned*)((const char*)(gbase) + (voff)[_i]), (PG8_LAS unsigned*)(lds + (bufoff) + ldsw + _i * 8192), 16, 0, 0); } while (0)
; #define PG8_LDA(dst, b, h) do { _Pragma("unroll") for (int m = 0; m < 4; ++m) _Pragma("unroll") for (int k = 0; k < 2; ++k) dst[m][k] = *(const PG8_LAS bf16x8*)(lds + PG8_SA(b, h) + aoff + m * 2048 + k * 1024); } while (0)
; #define PG8_LDB(dst, b, h) do { _Pragma("unroll") for (int n = 0; n < 2; ++n) _Pragma("unroll") for (int k = 0; k < 2; ++k) dst[n][k] = *(const PG8_LAS bf16x8*)(lds + PG8_SB(b, h) + boff + n * 2048 + k * 1024); } while (0)
; #define PG8_MMA(ai, bj, At, Bt) do { __builtin_amdgcn_s_setprio(1); _Pragma("unroll") for (int m = 0; m < 4; ++m) _Pragma("unroll") for (int n = 0; n < 2; ++n) _Pragma("unroll") for (int k = 0; k < 2; ++k) \
;         acc[ai][bj][m][n] = __builtin_amdgcn_mfma_f32_16x16x32_bf16(Bt[n][k], At[m][k], acc[ai][bj][m][n], 0, 0, 0); __builtin_amdgcn_s_setprio(0); } while (0)
; #define PG8_WAIT_V(n) asm volatile("s_waitcnt vmcnt(" #n ")" ::: "memory")
; #define PG8_WAIT_L(n) asm volatile("s_waitcnt lgkmcnt(" #n ")" ::: "memory")
; #define PG8_BAR __builtin_amdgcn_s_barrier()
; #define PG8_SCHED __builtin_amdgcn_sched_barrier(0)
; template <class Epi, class Sched, bool ALIGN_EPI = false, bool SP2 = false>
; __device__ __forceinline__ void gemm_phase(PG8_LAS unsigned char* lds, const Gemm g, const Sched& S, const Epi& E) {
;     ...
;             PG8_WAIT_V(8); PG8_WAIT_L(0); PG8_BAR; PG8_MMA(1, 0, At, B0); PG8_MMA(1, 1, At, B1); PG8_BAR; PG8_SCHED;
;             PG8_LDB(B0, 1, 0); PG8_LDB(B1, 1, 1); PG8_SCHED; PG8_LDA(At, 1, 0); PG8_STAGE(PG8_SA(0, 1), a2 + hstep, voffA);
;             PG8_WAIT_V(8); PG8_WAIT_L(0); PG8_BAR; PG8_MMA(0, 0, At, B0); PG8_MMA(0, 1, At, B1); PG8_BAR; PG8_SCHED;
	s_setprio 1
	s_waitcnt lgkmcnt(0)
	v_mfma_f32_16x16x32_bf16 v[62:65], v[152:155], v[188:191], v[62:65]
	v_mfma_f32_16x16x32_bf16 v[62:65], v[160:163], v[192:195], v[62:65]
	v_mfma_f32_16x16x32_bf16 v[58:61], v[164:167], v[188:191], v[58:61]
	v_mfma_f32_16x16x32_bf16 v[58:61], v[168:171], v[192:195], v[58:61]
	v_mfma_f32_16x16x32_bf16 v[50:53], v[152:155], v[196:199], v[50:53]
	v_mfma_f32_16x16x32_bf16 v[50:53], v[160:163], v[216:219], v[50:53]
	v_mfma_f32_16x16x32_bf16 v[42:45], v[164:167], v[196:199], v[42:45]
	v_mfma_f32_16x16x32_bf16 v[42:45], v[168:171], v[216:219], v[42:45]
	v_mfma_f32_16x16x32_bf16 v[34:37], v[152:155], v[220:223], v[34:37]
	v_mfma_f32_16x16x32_bf16 v[34:37], v[160:163], v[224:227], v[34:37]
	v_mfma_f32_16x16x32_bf16 v[26:29], v[164:167], v[220:223], v[26:29]
	v_mfma_f32_16x16x32_bf16 v[26:29], v[168:171], v[224:227], v[26:29]
	v_mfma_f32_16x16x32_bf16 v[18:21], v[152:155], v[228:231], v[18:21]
	v_mfma_f32_16x16x32_bf16 v[18:21], v[160:163], v[232:235], v[18:21]
	v_mfma_f32_16x16x32_bf16 v[10:13], v[164:167], v[228:231], v[10:13]
	v_mfma_f32_16x16x32_bf16 v[10:13], v[168:171], v[232:235], v[10:13]
	s_setprio 0
	s_setprio 1
	v_mfma_f32_16x16x32_bf16 v[54:57], v[172:175], v[188:191], v[54:57]
	v_mfma_f32_16x16x32_bf16 v[54:57], v[176:179], v[192:195], v[54:57]
	v_mfma_f32_16x16x32_bf16 v[46:49], v[180:183], v[188:191], v[46:49]
	v_mfma_f32_16x16x32_bf16 v[46:49], v[184:187], v[192:195], v[46:49]
	v_mfma_f32_16x16x32_bf16 v[38:41], v[172:175], v[196:199], v[38:41]
	v_mfma_f32_16x16x32_bf16 v[38:41], v[176:179], v[216:219], v[38:41]
	v_mfma_f32_16x16x32_bf16 v[30:33], v[180:183], v[196:199], v[30:33]
	v_mfma_f32_16x16x32_bf16 v[30:33], v[184:187], v[216:219], v[30:33]
	v_mfma_f32_16x16x32_bf16 v[22:25], v[172:175], v[220:223], v[22:25]
	v_mfma_f32_16x16x32_bf16 v[22:25], v[176:179], v[224:227], v[22:25]
	v_mfma_f32_16x16x32_bf16 v[14:17], v[180:183], v[220:223], v[14:17]
	v_mfma_f32_16x16x32_bf16 v[14:17], v[184:187], v[224:227], v[14:17]
	v_mfma_f32_16x16x32_bf16 v[6:9], v[172:175], v[228:231], v[6:9]
	v_mfma_f32_16x16x32_bf16 v[6:9], v[176:179], v[232:235], v[6:9]
	v_mfma_f32_16x16x32_bf16 v[2:5], v[180:183], v[228:231], v[2:5]
	v_mfma_f32_16x16x32_bf16 v[2:5], v[184:187], v[232:235], v[2:5]
	s_setprio 0
	s_barrier
	s_add_i32 s10, 0, 0x18000
	s_add_i32 s11, 0, 0x1c000
	v_add_u32_e32 v168, s10, v157
	v_add_u32_e32 v184, s11, v157
	ds_read_b128 v[152:155], v168
	ds_read_b128 v[160:163], v168 offset:1024
	ds_read_b128 v[164:167], v168 offset:2048
	ds_read_b128 v[168:171], v168 offset:3072
	ds_read_b128 v[172:175], v184
	ds_read_b128 v[176:179], v184 offset:1024
	ds_read_b128 v[180:183], v184 offset:2048
	ds_read_b128 v[184:187], v184 offset:3072
	s_add_u32 s38, s50, 0x80000
	s_addc_u32 s39, s51, 0
	s_mov_b32 m0, s59
	v_lshl_add_u64 v[242:243], s[38:39], 0, v[146:147]
	ds_read_b128 v[188:191], v159 offset:32768
	ds_read_b128 v[192:195], v159 offset:33792
	ds_read_b128 v[196:199], v159 offset:34816
	ds_read_b128 v[216:219], v159 offset:35840
	ds_read_b128 v[220:223], v159 offset:36864
	ds_read_b128 v[224:227], v159 offset:37888
	ds_read_b128 v[228:231], v159 offset:38912
	ds_read_b128 v[232:235], v159 offset:39936
	global_load_lds_dwordx4 v[242:243], off
	v_lshl_add_u64 v[242:243], s[38:39], 0, v[144:145]
	s_mov_b32 m0, s60
	s_nop 0
	global_load_lds_dwordx4 v[242:243], off
	s_waitcnt vmcnt(8)
	s_waitcnt lgkmcnt(0)
	s_barrier
	s_setprio 1
	s_waitcnt lgkmcnt(0)
	v_mfma_f32_16x16x32_bf16 v[126:129], v[152:155], v[188:191], v[126:129]
	v_mfma_f32_16x16x32_bf16 v[126:129], v[160:163], v[192:195], v[126:129]
	v_mfma_f32_16x16x32_bf16 v[122:125], v[164:167], v[188:191], v[122:125]
	v_mfma_f32_16x16x32_bf16 v[122:125], v[168:171], v[192:195], v[122:125]
	v_mfma_f32_16x16x32_bf16 v[110:113], v[152:155], v[196:199], v[110:113]
	v_mfma_f32_16x16x32_bf16 v[110:113], v[160:163], v[216:219], v[110:113]
	v_mfma_f32_16x16x32_bf16 v[106:109], v[164:167], v[196:199], v[106:109]
	v_mfma_f32_16x16x32_bf16 v[106:109], v[168:171], v[216:219], v[106:109]
	v_mfma_f32_16x16x32_bf16 v[94:97], v[152:155], v[220:223], v[94:97]
	v_mfma_f32_16x16x32_bf16 v[94:97], v[160:163], v[224:227], v[94:97]
	v_mfma_f32_16x16x32_bf16 v[90:93], v[164:167], v[220:223], v[90:93]
	v_mfma_f32_16x16x32_bf16 v[90:93], v[168:171], v[224:227], v[90:93]
	v_mfma_f32_16x16x32_bf16 v[78:81], v[152:155], v[228:231], v[78:81]
	v_mfma_f32_16x16x32_bf16 v[78:81], v[160:163], v[232:235], v[78:81]
	v_mfma_f32_16x16x32_bf16 v[74:77], v[164:167], v[228:231], v[74:77]
	v_mfma_f32_16x16x32_bf16 v[74:77], v[168:171], v[232:235], v[74:77]
	s_setprio 0
	s_setprio 1
	v_mfma_f32_16x16x32_bf16 v[118:121], v[172:175], v[188:191], v[118:121]
	v_mfma_f32_16x16x32_bf16 v[118:121], v[176:179], v[192:195], v[118:121]
	v_mfma_f32_16x16x32_bf16 v[114:117], v[180:183], v[188:191], v[114:117]
	v_mfma_f32_16x16x32_bf16 v[114:117], v[184:187], v[192:195], v[114:117]
	v_mfma_f32_16x16x32_bf16 v[102:105], v[172:175], v[196:199], v[102:105]
	v_mfma_f32_16x16x32_bf16 v[102:105], v[176:179], v[216:219], v[102:105]
	v_mfma_f32_16x16x32_bf16 v[98:101], v[180:183], v[196:199], v[98:101]
	v_mfma_f32_16x16x32_bf16 v[98:101], v[184:187], v[216:219], v[98:101]
	v_mfma_f32_16x16x32_bf16 v[86:89], v[172:175], v[220:223], v[86:89]
	v_mfma_f32_16x16x32_bf16 v[86:89], v[176:179], v[224:227], v[86:89]
	v_mfma_f32_16x16x32_bf16 v[82:85], v[180:183], v[220:223], v[82:85]
	v_mfma_f32_16x16x32_bf16 v[82:85], v[184:187], v[224:227], v[82:85]
	v_mfma_f32_16x16x32_bf16 v[70:73], v[172:175], v[228:231], v[70:73]
	v_mfma_f32_16x16x32_bf16 v[70:73], v[176:179], v[232:235], v[70:73]
	v_mfma_f32_16x16x32_bf16 v[66:69], v[180:183], v[228:231], v[66:69]
	v_mfma_f32_16x16x32_bf16 v[66:69], v[184:187], v[232:235], v[66:69]
	s_setprio 0
	s_barrier
; #define PG8_STAGE(bufoff, gbase, voff) do { _Pragma("unroll") for (int _i = 0; _i < 2; ++_i) \
;         __builtin_amdgcn_global_load_lds((const unsigned*)((const char*)(gbase) + (voff)[_i]), (PG8_LAS unsigned*)(lds + (bufoff) + ldsw + _i * 8192), 16, 0, 0); } while (0)
; #define PG8_LDA(dst, b, h) do { _Pragma("unroll") for (int m = 0; m < 4; ++m) _Pragma("unroll") for (int k = 0; k < 2; ++k) dst[m][k] = *(const PG8_LAS bf16x8*)(lds + PG8_SA(b, h) + aoff + m * 2048 + k * 1024); } while (0)
; #define PG8_MMA(ai, bj, At, Bt) do { __builtin_amdgcn_s_setprio(1); _Pragma("unroll") for (int m = 0; m < 4; ++m) _Pragma("unroll") for (int n = 0; n < 2; ++n) _Pragma("unroll") for (int k = 0; k < 2; ++k) \
;         acc[ai][bj][m][n] = __builtin_amdgcn_mfma_f32_16x16x32_bf16(Bt[n][k], At[m][k], acc[ai][bj][m][n], 0, 0, 0); __builtin_amdgcn_s_setprio(0); } while (0)
; #define PG8_WAIT_V(n) asm volatile("s_waitcnt vmcnt(" #n ")" ::: "memory")
; #define PG8_WAIT_L(n) asm volatile("s_waitcnt lgkmcnt(" #n ")" ::: "memory")
; #define PG8_BAR __builtin_amdgcn_s_barrier()
; #define PG8_SCHED __builtin_amdgcn_sched_barrier(0)
; template <class Epi, class Sched, bool ALIGN_EPI = false, bool SP2 = false>
; __device__ __forceinline__ void gemm_phase(PG8_LAS unsigned char* lds, const Gemm g, const Sched& S, const Epi& E) {
;     ...
;             PG8_LDA(At, 1, 1); PG8_STAGE(PG8_SB(1, 0), b3, voffB); PG8_STAGE(PG8_SB(1, 1), b3 + hstep, voffB); PG8_STAGE(PG8_SA(1, 0), a3, voffA);
;             PG8_WAIT_V(8); PG8_WAIT_L(0); PG8_BAR; PG8_MMA(1, 0, At, B0); PG8_MMA(1, 1, At, B1); PG8_BAR; PG8_SCHED;
;     ...
;         if constexpr (ALIGN_EPI) { if (wr == 0) PG8_BAR; }
	s_add_i32 s10, s10, s56
	v_lshl_add_u64 v[200:201], v[200:201], 0, s[30:31]
	s_mov_b32 m0, s10
	ds_read_b128 v[188:191], v159 offset:49152
	ds_read_b128 v[192:195], v159 offset:50176
	ds_read_b128 v[196:199], v159 offset:51200
	ds_read_b128 v[216:219], v159 offset:52224
	ds_read_b128 v[220:223], v159 offset:53248
	ds_read_b128 v[224:227], v159 offset:54272
	ds_read_b128 v[228:231], v159 offset:55296
	ds_read_b128 v[232:235], v159 offset:56320
	global_load_lds_dwordx4 v[200:201], off
	s_add_i32 m0, s10, 0x2000
	s_add_u32 s18, s18, 0x80080
	v_lshl_add_u64 v[200:201], v[236:237], 0, s[30:31]
	s_addc_u32 s19, s19, 0
	s_add_i32 s10, s11, s56
	global_load_lds_dwordx4 v[200:201], off
	v_lshl_add_u64 v[200:201], s[18:19], 0, v[0:1]
	s_mov_b32 m0, s10
	s_nop 0
	global_load_lds_dwordx4 v[200:201], off
	v_lshl_add_u64 v[200:201], s[18:19], 0, v[142:143]
	s_add_i32 m0, s10, 0x2000
	s_nop 0
	global_load_lds_dwordx4 v[200:201], off
	v_lshl_add_u64 v[200:201], v[238:239], 0, s[30:31]
	s_mov_b32 m0, s61
	s_nop 0
	global_load_lds_dwordx4 v[200:201], off
	v_lshl_add_u64 v[200:201], v[240:241], 0, s[30:31]
	s_mov_b32 m0, s62
	s_nop 0
	global_load_lds_dwordx4 v[200:201], off
	s_waitcnt vmcnt(8)
	s_waitcnt lgkmcnt(0)
	s_barrier
	s_setprio 1
	s_waitcnt lgkmcnt(0)
	v_mfma_f32_16x16x32_bf16 v[62:65], v[152:155], v[188:191], v[62:65]
	v_mfma_f32_16x16x32_bf16 v[62:65], v[160:163], v[192:195], v[62:65]
	v_mfma_f32_16x16x32_bf16 v[58:61], v[164:167], v[188:191], v[58:61]
	v_mfma_f32_16x16x32_bf16 v[58:61], v[168:171], v[192:195], v[58:61]
	v_mfma_f32_16x16x32_bf16 v[50:53], v[152:155], v[196:199], v[50:53]
	v_mfma_f32_16x16x32_bf16 v[50:53], v[160:163], v[216:219], v[50:53]
	v_mfma_f32_16x16x32_bf16 v[42:45], v[164:167], v[196:199], v[42:45]
	v_mfma_f32_16x16x32_bf16 v[42:45], v[168:171], v[216:219], v[42:45]
	v_mfma_f32_16x16x32_bf16 v[34:37], v[152:155], v[220:223], v[34:37]
	v_mfma_f32_16x16x32_bf16 v[34:37], v[160:163], v[224:227], v[34:37]
	v_mfma_f32_16x16x32_bf16 v[26:29], v[164:167], v[220:223], v[26:29]
	v_mfma_f32_16x16x32_bf16 v[26:29], v[168:171], v[224:227], v[26:29]
	v_mfma_f32_16x16x32_bf16 v[18:21], v[152:155], v[228:231], v[18:21]
	v_mfma_f32_16x16x32_bf16 v[18:21], v[160:163], v[232:235], v[18:21]
	v_mfma_f32_16x16x32_bf16 v[10:13], v[164:167], v[228:231], v[10:13]
	v_mfma_f32_16x16x32_bf16 v[10:13], v[168:171], v[232:235], v[10:13]
	s_setprio 0
	s_setprio 1
	v_mfma_f32_16x16x32_bf16 v[54:57], v[172:175], v[188:191], v[54:57]
	v_mfma_f32_16x16x32_bf16 v[54:57], v[176:179], v[192:195], v[54:57]
	v_mfma_f32_16x16x32_bf16 v[46:49], v[180:183], v[188:191], v[46:49]
	v_mfma_f32_16x16x32_bf16 v[46:49], v[184:187], v[192:195], v[46:49]
	v_mfma_f32_16x16x32_bf16 v[38:41], v[172:175], v[196:199], v[38:41]
	v_mfma_f32_16x16x32_bf16 v[38:41], v[176:179], v[216:219], v[38:41]
	v_mfma_f32_16x16x32_bf16 v[30:33], v[180:183], v[196:199], v[30:33]
	v_mfma_f32_16x16x32_bf16 v[30:33], v[184:187], v[216:219], v[30:33]
	v_mfma_f32_16x16x32_bf16 v[22:25], v[172:175], v[220:223], v[22:25]
	v_mfma_f32_16x16x32_bf16 v[22:25], v[176:179], v[224:227], v[22:25]
	v_mfma_f32_16x16x32_bf16 v[14:17], v[180:183], v[220:223], v[14:17]
	v_mfma_f32_16x16x32_bf16 v[14:17], v[184:187], v[224:227], v[14:17]
	v_mfma_f32_16x16x32_bf16 v[6:9], v[172:175], v[228:231], v[6:9]
	v_mfma_f32_16x16x32_bf16 v[6:9], v[176:179], v[232:235], v[6:9]
	v_mfma_f32_16x16x32_bf16 v[2:5], v[180:183], v[228:231], v[2:5]
	v_mfma_f32_16x16x32_bf16 v[2:5], v[184:187], v[232:235], v[2:5]
	s_setprio 0
	s_barrier
	s_add_i32 s23, s23, 2
	s_add_u32 s16, s16, 0x100
	s_addc_u32 s17, s17, 0
	s_add_u32 s15, s15, 0x100
	s_addc_u32 s22, s22, 0
	s_cmp_gt_u32 s23, 29
	s_cbranch_scc0 .LBB0_265
	s_and_b64 vcc, exec, s[24:25]
	s_cbranch_vccz .LBB0_268
	s_barrier

; #define PG8_STAGE(bufoff, gbase, voff) do { _Pragma("unroll") for (int _i = 0; _i < 2; ++_i) \
;         __builtin_amdgcn_global_load_lds((const unsigned*)((const char*)(gbase) + (voff)[_i]), (PG8_LAS unsigned*)(lds + (bufoff) + ldsw + _i * 8192), 16, 0, 0); } while (0)
; #define PG8_LDA(dst, b, h) do { _Pragma("unroll") for (int m = 0; m < 4; ++m) _Pragma("unroll") for (int k = 0; k < 2; ++k) dst[m][k] = *(const PG8_LAS bf16x8*)(lds + PG8_SA(b, h) + aoff + m * 2048 + k * 1024); } while (0)
; #define PG8_LDB(dst, b, h) do { _Pragma("unroll") for (int n = 0; n < 2; ++n) _Pragma("unroll") for (int k = 0; k < 2; ++k) dst[n][k] = *(const PG8_LAS bf16x8*)(lds + PG8_SB(b, h) + boff + n * 2048 + k * 1024); } while (0)
; #define PG8_MMA(ai, bj, At, Bt) do { __builtin_amdgcn_s_setprio(1); _Pragma("unroll") for (int m = 0; m < 4; ++m) _Pragma("unroll") for (int n = 0; n < 2; ++n) _Pragma("unroll") for (int k = 0; k < 2; ++k) \
;         acc[ai][bj][m][n] = __builtin_amdgcn_mfma_f32_16x16x32_bf16(Bt[n][k], At[m][k], acc[ai][bj][m][n], 0, 0, 0); __builtin_amdgcn_s_setprio(0); } while (0)
; #define PG8_WAIT_V(n) asm volatile("s_waitcnt vmcnt(" #n ")" ::: "memory")
; #define PG8_WAIT_L(n) asm volatile("s_waitcnt lgkmcnt(" #n ")" ::: "memory")
; template <class Epi, class Sched, bool ALIGN_EPI = false, bool SP2 = false>
; __device__ __forceinline__ void gemm_phase(PG8_LAS unsigned char* lds, const Gemm g, const Sched& S, const Epi& E) {
;     ...
;             const bool last = (t == nt - 2);
;             const char* a1 = cA + (size_t)(t + 1) * kstep;
;             const char* a2 = last ? nA : cA + (size_t)(t + 2) * kstep; const char* b2 = last ? nB : cB + (size_t)(t + 2) * kstep;
;             const char* a3 = a2 + kstep; const char* b3 = b2 + kstep;
;             if (last && has_next) S.a_ready(nxt);
;             if constexpr (SP2) {
;             PG8_LDB(B0, 0, 0); PG8_LDB(B1, 0, 1); PG8_SCHED; PG8_LDA(At, 0, 0); PG8_STAGE(PG8_SA(1, 1), a1 + hstep, voffA);
;             PG8_WAIT_V(8); PG8_WAIT_L(0); PG8_BAR; PG8_MMA(0, 0, At, B0); PG8_MMA(0, 1, At, B1); PG8_BAR; PG8_SCHED;
;             PG8_LDA(At, 0, 1); PG8_STAGE(PG8_SB(0, 0), b2, voffB); PG8_STAGE(PG8_SB(0, 1), b2 + hstep, voffB); PG8_STAGE(PG8_SA(0, 0), a2, voffA);
;             PG8_WAIT_V(8); PG8_WAIT_L(0); PG8_BAR; PG8_MMA(1, 0, At, B0); PG8_MMA(1, 1, At, B1); PG8_BAR; PG8_SCHED;
.LBB0_601:
	s_add_u32 s18, s16, 0x100
	s_addc_u32 s19, s17, 0
	s_add_i32 s10, 0, 0x10000
	s_cmp_eq_u32 s22, 28
	s_cselect_b32 s27, s5, s19
	s_cselect_b32 s26, s7, s18
	s_cselect_b32 s25, s8, s15
	s_cselect_b32 s24, s9, s14
	s_add_i32 s12, 0, 0x14000
	v_add_u32_e32 v160, s10, v187
	v_add_u32_e32 v176, s12, v187
	ds_read_b128 v[148:151], v160
	ds_read_b128 v[152:155], v160 offset:1024
	ds_read_b128 v[156:159], v160 offset:2048
	ds_read_b128 v[160:163], v160 offset:3072
	ds_read_b128 v[164:167], v176
	ds_read_b128 v[168:171], v176 offset:1024
	ds_read_b128 v[172:175], v176 offset:2048
	ds_read_b128 v[176:179], v176 offset:3072
	v_lshl_add_u64 v[184:185], s[16:17], 0, v[144:145]
	s_add_i32 m0, s61, 0xc000
	ds_read_b128 v[180:183], v189
	ds_read_b128 v[190:193], v189 offset:1024
	ds_read_b128 v[194:197], v189 offset:2048
	ds_read_b128 v[198:201], v189 offset:3072
	ds_read_b128 v[216:219], v189 offset:4096
	ds_read_b128 v[220:223], v189 offset:5120
	ds_read_b128 v[224:227], v189 offset:6144
	ds_read_b128 v[228:231], v189 offset:7168
	global_load_lds_dwordx4 v[184:185], off
	v_lshl_add_u64 v[184:185], s[16:17], 0, v[146:147]
	s_add_i32 m0, s61, 0xe000
	s_nop 0
	global_load_lds_dwordx4 v[184:185], off
	s_waitcnt vmcnt(8)
	s_waitcnt lgkmcnt(0)
	s_barrier
	s_setprio 1
	s_waitcnt lgkmcnt(0)
	v_mfma_f32_16x16x32_bf16 v[126:129], v[148:151], v[180:183], v[126:129]
	v_mfma_f32_16x16x32_bf16 v[126:129], v[152:155], v[190:193], v[126:129]
	v_mfma_f32_16x16x32_bf16 v[122:125], v[156:159], v[180:183], v[122:125]
	v_mfma_f32_16x16x32_bf16 v[122:125], v[160:163], v[190:193], v[122:125]
	v_mfma_f32_16x16x32_bf16 v[110:113], v[148:151], v[194:197], v[110:113]
	v_mfma_f32_16x16x32_bf16 v[110:113], v[152:155], v[198:201], v[110:113]
	v_mfma_f32_16x16x32_bf16 v[106:109], v[156:159], v[194:197], v[106:109]
	v_mfma_f32_16x16x32_bf16 v[106:109], v[160:163], v[198:201], v[106:109]
	v_mfma_f32_16x16x32_bf16 v[94:97], v[148:151], v[216:219], v[94:97]
	v_mfma_f32_16x16x32_bf16 v[94:97], v[152:155], v[220:223], v[94:97]
	v_mfma_f32_16x16x32_bf16 v[90:93], v[156:159], v[216:219], v[90:93]
	v_mfma_f32_16x16x32_bf16 v[90:93], v[160:163], v[220:223], v[90:93]
	v_mfma_f32_16x16x32_bf16 v[78:81], v[148:151], v[224:227], v[78:81]
	v_mfma_f32_16x16x32_bf16 v[78:81], v[152:155], v[228:231], v[78:81]
	v_mfma_f32_16x16x32_bf16 v[74:77], v[156:159], v[224:227], v[74:77]
	v_mfma_f32_16x16x32_bf16 v[74:77], v[160:163], v[228:231], v[74:77]
	s_setprio 0
	s_setprio 1
	v_mfma_f32_16x16x32_bf16 v[118:121], v[164:167], v[180:183], v[118:121]
	v_mfma_f32_16x16x32_bf16 v[118:121], v[168:171], v[190:193], v[118:121]
	v_mfma_f32_16x16x32_bf16 v[114:117], v[172:175], v[180:183], v[114:117]
	v_mfma_f32_16x16x32_bf16 v[114:117], v[176:179], v[190:193], v[114:117]
	v_mfma_f32_16x16x32_bf16 v[102:105], v[164:167], v[194:197], v[102:105]
	v_mfma_f32_16x16x32_bf16 v[102:105], v[168:171], v[198:201], v[102:105]
	v_mfma_f32_16x16x32_bf16 v[98:101], v[172:175], v[194:197], v[98:101]
	v_mfma_f32_16x16x32_bf16 v[98:101], v[176:179], v[198:201], v[98:101]
	v_mfma_f32_16x16x32_bf16 v[86:89], v[164:167], v[216:219], v[86:89]
	v_mfma_f32_16x16x32_bf16 v[86:89], v[168:171], v[220:223], v[86:89]
	v_mfma_f32_16x16x32_bf16 v[82:85], v[172:175], v[216:219], v[82:85]
	v_mfma_f32_16x16x32_bf16 v[82:85], v[176:179], v[220:223], v[82:85]
	v_mfma_f32_16x16x32_bf16 v[70:73], v[164:167], v[224:227], v[70:73]
	v_mfma_f32_16x16x32_bf16 v[70:73], v[168:171], v[228:231], v[70:73]
	v_mfma_f32_16x16x32_bf16 v[66:69], v[172:175], v[224:227], v[66:69]
	v_mfma_f32_16x16x32_bf16 v[66:69], v[176:179], v[228:231], v[66:69]
	s_setprio 0
	s_barrier
	s_add_i32 s10, s10, s60
	v_lshl_add_u64 v[184:185], s[24:25], 0, v[0:1]
	s_mov_b32 m0, s10
	ds_read_b128 v[180:183], v189 offset:16384
	ds_read_b128 v[190:193], v189 offset:17408
	ds_read_b128 v[194:197], v189 offset:18432
	ds_read_b128 v[198:201], v189 offset:19456
	ds_read_b128 v[216:219], v189 offset:20480
	ds_read_b128 v[220:223], v189 offset:21504
	ds_read_b128 v[224:227], v189 offset:22528
	ds_read_b128 v[228:231], v189 offset:23552
	global_load_lds_dwordx4 v[184:185], off
	s_add_i32 m0, s10, 0x2000
	s_add_u32 s10, s24, 0x80000
	v_lshl_add_u64 v[232:233], s[24:25], 0, v[142:143]
	s_addc_u32 s11, s25, 0
	s_add_i32 s12, s12, s60
	global_load_lds_dwordx4 v[232:233], off
	v_lshl_add_u64 v[234:235], s[10:11], 0, v[0:1]
	s_mov_b32 m0, s12
	v_lshl_add_u64 v[236:237], s[26:27], 0, v[142:143]
	global_load_lds_dwordx4 v[234:235], off
	v_lshl_add_u64 v[234:235], s[10:11], 0, v[142:143]
	s_add_i32 m0, s12, 0x2000
	s_nop 0
	global_load_lds_dwordx4 v[234:235], off
	v_lshl_add_u64 v[234:235], s[26:27], 0, v[0:1]
	s_mov_b32 m0, s61
	s_nop 0
	global_load_lds_dwordx4 v[234:235], off
	s_mov_b32 m0, s62
	s_nop 0
	global_load_lds_dwordx4 v[236:237], off
	s_waitcnt vmcnt(8)
	s_waitcnt lgkmcnt(0)
	s_barrier
; #define PG8_STAGE(bufoff, gbase, voff) do { _Pragma("unroll") for (int _i = 0; _i < 2; ++_i) \
;         __builtin_amdgcn_global_load_lds((const unsigned*)((const char*)(gbase) + (voff)[_i]), (PG8_LAS unsigned*)(lds + (bufoff) + ldsw + _i * 8192), 16, 0, 0); } while (0)
; #define PG8_LDA(dst, b, h) do { _Pragma("unroll") for (int m = 0; m < 4; ++m) _Pragma("unroll") for (int k = 0; k < 2; ++k) dst[m][k] = *(const PG8_LAS bf16x8*)(lds + PG8_SA(b, h) + aoff + m * 2048 + k * 1024); } while (0)
; #define PG8_LDB(dst, b, h) do { _Pragma("unroll") for (int n = 0; n < 2; ++n) _Pragma("unroll") for (int k = 0; k < 2; ++k) dst[n][k] = *(const PG8_LAS bf16x8*)(lds + PG8_SB(b, h) + boff + n * 2048 + k * 1024); } while (0)
; #define PG8_MMA(ai, bj, At, Bt) do { __builtin_amdgcn_s_setprio(1); _Pragma("unroll") for (int m = 0; m < 4; ++m) _Pragma("unroll") for (int n = 0; n < 2; ++n) _Pragma("unroll") for (int k = 0; k < 2; ++k) \
;         acc[ai][bj][m][n] = __builtin_amdgcn_mfma_f32_16x16x32_bf16(Bt[n][k], At[m][k], acc[ai][bj][m][n], 0, 0, 0); __builtin_amdgcn_s_setprio(0); } while (0)
; #define PG8_WAIT_V(n) asm volatile("s_waitcnt vmcnt(" #n ")" ::: "memory")
; #define PG8_WAIT_L(n) asm volatile("s_waitcnt lgkmcnt(" #n ")" ::: "memory")
; #define PG8_BAR __builtin_amdgcn_s_barrier()
; #define PG8_SCHED __builtin_amdgcn_sched_barrier(0)
; template <class Epi, class Sched, bool ALIGN_EPI = false, bool SP2 = false>
; __device__ __forceinline__ void gemm_phase(PG8_LAS unsigned char* lds, const Gemm g, const Sched& S, const Epi& E) {
;     ...
;             PG8_WAIT_V(8); PG8_WAIT_L(0); PG8_BAR; PG8_MMA(1, 0, At, B0); PG8_MMA(1, 1, At, B1); PG8_BAR; PG8_SCHED;
;             PG8_LDB(B0, 1, 0); PG8_LDB(B1, 1, 1); PG8_SCHED; PG8_LDA(At, 1, 0); PG8_STAGE(PG8_SA(0, 1), a2 + hstep, voffA);
;             PG8_WAIT_V(8); PG8_WAIT_L(0); PG8_BAR; PG8_MMA(0, 0, At, B0); PG8_MMA(0, 1, At, B1); PG8_BAR; PG8_SCHED;
	s_setprio 1
	s_waitcnt lgkmcnt(0)
	v_mfma_f32_16x16x32_bf16 v[62:65], v[148:151], v[180:183], v[62:65]
	v_mfma_f32_16x16x32_bf16 v[62:65], v[152:155], v[190:193], v[62:65]
	v_mfma_f32_16x16x32_bf16 v[58:61], v[156:159], v[180:183], v[58:61]
	v_mfma_f32_16x16x32_bf16 v[58:61], v[160:163], v[190:193], v[58:61]
	v_mfma_f32_16x16x32_bf16 v[46:49], v[148:151], v[194:197], v[46:49]
	v_mfma_f32_16x16x32_bf16 v[46:49], v[152:155], v[198:201], v[46:49]
	v_mfma_f32_16x16x32_bf16 v[42:45], v[156:159], v[194:197], v[42:45]
	v_mfma_f32_16x16x32_bf16 v[42:45], v[160:163], v[198:201], v[42:45]
	v_mfma_f32_16x16x32_bf16 v[30:33], v[148:151], v[216:219], v[30:33]
	v_mfma_f32_16x16x32_bf16 v[30:33], v[152:155], v[220:223], v[30:33]
	v_mfma_f32_16x16x32_bf16 v[26:29], v[156:159], v[216:219], v[26:29]
	v_mfma_f32_16x16x32_bf16 v[26:29], v[160:163], v[220:223], v[26:29]
	v_mfma_f32_16x16x32_bf16 v[14:17], v[148:151], v[224:227], v[14:17]
	v_mfma_f32_16x16x32_bf16 v[14:17], v[152:155], v[228:231], v[14:17]
	v_mfma_f32_16x16x32_bf16 v[10:13], v[156:159], v[224:227], v[10:13]
	v_mfma_f32_16x16x32_bf16 v[10:13], v[160:163], v[228:231], v[10:13]
	s_setprio 0
	s_setprio 1
	v_mfma_f32_16x16x32_bf16 v[54:57], v[164:167], v[180:183], v[54:57]
	v_mfma_f32_16x16x32_bf16 v[54:57], v[168:171], v[190:193], v[54:57]
	v_mfma_f32_16x16x32_bf16 v[50:53], v[172:175], v[180:183], v[50:53]
	v_mfma_f32_16x16x32_bf16 v[50:53], v[176:179], v[190:193], v[50:53]
	v_mfma_f32_16x16x32_bf16 v[38:41], v[164:167], v[194:197], v[38:41]
	v_mfma_f32_16x16x32_bf16 v[38:41], v[168:171], v[198:201], v[38:41]
	v_mfma_f32_16x16x32_bf16 v[34:37], v[172:175], v[194:197], v[34:37]
	v_mfma_f32_16x16x32_bf16 v[34:37], v[176:179], v[198:201], v[34:37]
	v_mfma_f32_16x16x32_bf16 v[22:25], v[164:167], v[216:219], v[22:25]
	v_mfma_f32_16x16x32_bf16 v[22:25], v[168:171], v[220:223], v[22:25]
	v_mfma_f32_16x16x32_bf16 v[18:21], v[172:175], v[216:219], v[18:21]
	v_mfma_f32_16x16x32_bf16 v[18:21], v[176:179], v[220:223], v[18:21]
	v_mfma_f32_16x16x32_bf16 v[6:9], v[164:167], v[224:227], v[6:9]
	v_mfma_f32_16x16x32_bf16 v[6:9], v[168:171], v[228:231], v[6:9]
	v_mfma_f32_16x16x32_bf16 v[2:5], v[172:175], v[224:227], v[2:5]
	v_mfma_f32_16x16x32_bf16 v[2:5], v[176:179], v[228:231], v[2:5]
	s_setprio 0
	s_barrier
	s_add_i32 s12, 0, 0x18000
	s_add_i32 s13, 0, 0x1c000
	v_add_u32_e32 v160, s12, v187
	v_add_u32_e32 v176, s13, v187
	ds_read_b128 v[148:151], v160
	ds_read_b128 v[152:155], v160 offset:1024
	ds_read_b128 v[156:159], v160 offset:2048
	ds_read_b128 v[160:163], v160 offset:3072
	ds_read_b128 v[164:167], v176
	ds_read_b128 v[168:171], v176 offset:1024
	ds_read_b128 v[172:175], v176 offset:2048
	ds_read_b128 v[176:179], v176 offset:3072
	s_add_u32 s10, s26, 0x80000
	s_addc_u32 s11, s27, 0
	s_mov_b32 m0, s63
	v_lshl_add_u64 v[238:239], s[10:11], 0, v[0:1]
	ds_read_b128 v[180:183], v189 offset:32768
	ds_read_b128 v[190:193], v189 offset:33792
	ds_read_b128 v[194:197], v189 offset:34816
	ds_read_b128 v[198:201], v189 offset:35840
	ds_read_b128 v[216:219], v189 offset:36864
	ds_read_b128 v[220:223], v189 offset:37888
	ds_read_b128 v[224:227], v189 offset:38912
	ds_read_b128 v[228:231], v189 offset:39936
	global_load_lds_dwordx4 v[238:239], off
	v_lshl_add_u64 v[238:239], s[10:11], 0, v[142:143]
	s_mov_b32 m0, s64
	s_nop 0
	global_load_lds_dwordx4 v[238:239], off
	s_waitcnt vmcnt(8)
	s_waitcnt lgkmcnt(0)
	s_barrier
	s_setprio 1
	s_waitcnt lgkmcnt(0)
	v_mfma_f32_16x16x32_bf16 v[126:129], v[148:151], v[180:183], v[126:129]
	v_mfma_f32_16x16x32_bf16 v[126:129], v[152:155], v[190:193], v[126:129]
	v_mfma_f32_16x16x32_bf16 v[122:125], v[156:159], v[180:183], v[122:125]
	v_mfma_f32_16x16x32_bf16 v[122:125], v[160:163], v[190:193], v[122:125]
	v_mfma_f32_16x16x32_bf16 v[110:113], v[148:151], v[194:197], v[110:113]
	v_mfma_f32_16x16x32_bf16 v[110:113], v[152:155], v[198:201], v[110:113]
	v_mfma_f32_16x16x32_bf16 v[106:109], v[156:159], v[194:197], v[106:109]
	v_mfma_f32_16x16x32_bf16 v[106:109], v[160:163], v[198:201], v[106:109]
	v_mfma_f32_16x16x32_bf16 v[94:97], v[148:151], v[216:219], v[94:97]
	v_mfma_f32_16x16x32_bf16 v[94:97], v[152:155], v[220:223], v[94:97]
	v_mfma_f32_16x16x32_bf16 v[90:93], v[156:159], v[216:219], v[90:93]
	v_mfma_f32_16x16x32_bf16 v[90:93], v[160:163], v[220:223], v[90:93]
	v_mfma_f32_16x16x32_bf16 v[78:81], v[148:151], v[224:227], v[78:81]
	v_mfma_f32_16x16x32_bf16 v[78:81], v[152:155], v[228:231], v[78:81]
	v_mfma_f32_16x16x32_bf16 v[74:77], v[156:159], v[224:227], v[74:77]
	v_mfma_f32_16x16x32_bf16 v[74:77], v[160:163], v[228:231], v[74:77]
	s_setprio 0
	s_setprio 1
	v_mfma_f32_16x16x32_bf16 v[118:121], v[164:167], v[180:183], v[118:121]
	v_mfma_f32_16x16x32_bf16 v[118:121], v[168:171], v[190:193], v[118:121]
	v_mfma_f32_16x16x32_bf16 v[114:117], v[172:175], v[180:183], v[114:117]
	v_mfma_f32_16x16x32_bf16 v[114:117], v[176:179], v[190:193], v[114:117]
	v_mfma_f32_16x16x32_bf16 v[102:105], v[164:167], v[194:197], v[102:105]
	v_mfma_f32_16x16x32_bf16 v[102:105], v[168:171], v[198:201], v[102:105]
	v_mfma_f32_16x16x32_bf16 v[98:101], v[172:175], v[194:197], v[98:101]
	v_mfma_f32_16x16x32_bf16 v[98:101], v[176:179], v[198:201], v[98:101]
	v_mfma_f32_16x16x32_bf16 v[86:89], v[164:167], v[216:219], v[86:89]
	v_mfma_f32_16x16x32_bf16 v[86:89], v[168:171], v[220:223], v[86:89]
	v_mfma_f32_16x16x32_bf16 v[82:85], v[172:175], v[216:219], v[82:85]
	v_mfma_f32_16x16x32_bf16 v[82:85], v[176:179], v[220:223], v[82:85]
	v_mfma_f32_16x16x32_bf16 v[70:73], v[164:167], v[224:227], v[70:73]
	v_mfma_f32_16x16x32_bf16 v[70:73], v[168:171], v[228:231], v[70:73]
	v_mfma_f32_16x16x32_bf16 v[66:69], v[172:175], v[224:227], v[66:69]
	v_mfma_f32_16x16x32_bf16 v[66:69], v[176:179], v[228:231], v[66:69]
	s_setprio 0
	s_barrier
; #define PG8_STAGE(bufoff, gbase, voff) do { _Pragma("unroll") for (int _i = 0; _i < 2; ++_i) \
;         __builtin_amdgcn_global_load_lds((const unsigned*)((const char*)(gbase) + (voff)[_i]), (PG8_LAS unsigned*)(lds + (bufoff) + ldsw + _i * 8192), 16, 0, 0); } while (0)
; #define PG8_LDA(dst, b, h) do { _Pragma("unroll") for (int m = 0; m < 4; ++m) _Pragma("unroll") for (int k = 0; k < 2; ++k) dst[m][k] = *(const PG8_LAS bf16x8*)(lds + PG8_SA(b, h) + aoff + m * 2048 + k * 1024); } while (0)
; #define PG8_MMA(ai, bj, At, Bt) do { __builtin_amdgcn_s_setprio(1); _Pragma("unroll") for (int m = 0; m < 4; ++m) _Pragma("unroll") for (int n = 0; n < 2; ++n) _Pragma("unroll") for (int k = 0; k < 2; ++k) \
;         acc[ai][bj][m][n] = __builtin_amdgcn_mfma_f32_16x16x32_bf16(Bt[n][k], At[m][k], acc[ai][bj][m][n], 0, 0, 0); __builtin_amdgcn_s_setprio(0); } while (0)
; #define PG8_WAIT_V(n) asm volatile("s_waitcnt vmcnt(" #n ")" ::: "memory")
; #define PG8_WAIT_L(n) asm volatile("s_waitcnt lgkmcnt(" #n ")" ::: "memory")
; #define PG8_BAR __builtin_amdgcn_s_barrier()
; #define PG8_SCHED __builtin_amdgcn_sched_barrier(0)
; template <class Epi, class Sched, bool ALIGN_EPI = false, bool SP2 = false>
; __device__ __forceinline__ void gemm_phase(PG8_LAS unsigned char* lds, const Gemm g, const Sched& S, const Epi& E) {
;     ...
;             PG8_LDA(At, 1, 1); PG8_STAGE(PG8_SB(1, 0), b3, voffB); PG8_STAGE(PG8_SB(1, 1), b3 + hstep, voffB); PG8_STAGE(PG8_SA(1, 0), a3, voffA);
;             PG8_WAIT_V(8); PG8_WAIT_L(0); PG8_BAR; PG8_MMA(1, 0, At, B0); PG8_MMA(1, 1, At, B1); PG8_BAR; PG8_SCHED;
	s_add_i32 s10, s12, s60
	v_lshl_add_u64 v[184:185], v[184:185], 0, s[30:31]
	s_mov_b32 m0, s10
	ds_read_b128 v[180:183], v189 offset:49152
	ds_read_b128 v[190:193], v189 offset:50176
	ds_read_b128 v[194:197], v189 offset:51200
	ds_read_b128 v[198:201], v189 offset:52224
	ds_read_b128 v[216:219], v189 offset:53248
	ds_read_b128 v[220:223], v189 offset:54272
	ds_read_b128 v[224:227], v189 offset:55296
	ds_read_b128 v[228:231], v189 offset:56320
	global_load_lds_dwordx4 v[184:185], off
	s_add_i32 m0, s10, 0x2000
	s_add_u32 s10, s24, 0x80080
	v_lshl_add_u64 v[184:185], v[232:233], 0, s[30:31]
	s_addc_u32 s11, s25, 0
	s_add_i32 s12, s13, s60
	global_load_lds_dwordx4 v[184:185], off
	v_lshl_add_u64 v[184:185], s[10:11], 0, v[0:1]
	s_mov_b32 m0, s12
	s_nop 0
	global_load_lds_dwordx4 v[184:185], off
	v_lshl_add_u64 v[184:185], s[10:11], 0, v[142:143]
	s_add_i32 m0, s12, 0x2000
	s_nop 0
	global_load_lds_dwordx4 v[184:185], off
	v_lshl_add_u64 v[184:185], v[234:235], 0, s[30:31]
	s_mov_b32 m0, s65
	s_nop 0
	global_load_lds_dwordx4 v[184:185], off
	v_lshl_add_u64 v[184:185], v[236:237], 0, s[30:31]
	s_mov_b32 m0, s66
	s_nop 0
	global_load_lds_dwordx4 v[184:185], off
	s_waitcnt vmcnt(8)
	s_waitcnt lgkmcnt(0)
	s_barrier
	s_setprio 1
	s_waitcnt lgkmcnt(0)
	v_mfma_f32_16x16x32_bf16 v[62:65], v[148:151], v[180:183], v[62:65]
	v_mfma_f32_16x16x32_bf16 v[62:65], v[152:155], v[190:193], v[62:65]
	v_mfma_f32_16x16x32_bf16 v[58:61], v[156:159], v[180:183], v[58:61]
	v_mfma_f32_16x16x32_bf16 v[58:61], v[160:163], v[190:193], v[58:61]
	v_mfma_f32_16x16x32_bf16 v[46:49], v[148:151], v[194:197], v[46:49]
	v_mfma_f32_16x16x32_bf16 v[46:49], v[152:155], v[198:201], v[46:49]
	v_mfma_f32_16x16x32_bf16 v[42:45], v[156:159], v[194:197], v[42:45]
	v_mfma_f32_16x16x32_bf16 v[42:45], v[160:163], v[198:201], v[42:45]
	v_mfma_f32_16x16x32_bf16 v[30:33], v[148:151], v[216:219], v[30:33]
	v_mfma_f32_16x16x32_bf16 v[30:33], v[152:155], v[220:223], v[30:33]
	v_mfma_f32_16x16x32_bf16 v[26:29], v[156:159], v[216:219], v[26:29]
	v_mfma_f32_16x16x32_bf16 v[26:29], v[160:163], v[220:223], v[26:29]
	v_mfma_f32_16x16x32_bf16 v[14:17], v[148:151], v[224:227], v[14:17]
	v_mfma_f32_16x16x32_bf16 v[14:17], v[152:155], v[228:231], v[14:17]
	v_mfma_f32_16x16x32_bf16 v[10:13], v[156:159], v[224:227], v[10:13]
	v_mfma_f32_16x16x32_bf16 v[10:13], v[160:163], v[228:231], v[10:13]
	s_setprio 0
	s_setprio 1
	v_mfma_f32_16x16x32_bf16 v[54:57], v[164:167], v[180:183], v[54:57]
	v_mfma_f32_16x16x32_bf16 v[54:57], v[168:171], v[190:193], v[54:57]
	v_mfma_f32_16x16x32_bf16 v[50:53], v[172:175], v[180:183], v[50:53]
	v_mfma_f32_16x16x32_bf16 v[50:53], v[176:179], v[190:193], v[50:53]
	v_mfma_f32_16x16x32_bf16 v[38:41], v[164:167], v[194:197], v[38:41]
	v_mfma_f32_16x16x32_bf16 v[38:41], v[168:171], v[198:201], v[38:41]
	v_mfma_f32_16x16x32_bf16 v[34:37], v[172:175], v[194:197], v[34:37]
	v_mfma_f32_16x16x32_bf16 v[34:37], v[176:179], v[198:201], v[34:37]
	v_mfma_f32_16x16x32_bf16 v[22:25], v[164:167], v[216:219], v[22:25]
	v_mfma_f32_16x16x32_bf16 v[22:25], v[168:171], v[220:223], v[22:25]
	v_mfma_f32_16x16x32_bf16 v[18:21], v[172:175], v[216:219], v[18:21]
	v_mfma_f32_16x16x32_bf16 v[18:21], v[176:179], v[220:223], v[18:21]
	v_mfma_f32_16x16x32_bf16 v[6:9], v[164:167], v[224:227], v[6:9]
	v_mfma_f32_16x16x32_bf16 v[6:9], v[168:171], v[228:231], v[6:9]
	v_mfma_f32_16x16x32_bf16 v[2:5], v[172:175], v[224:227], v[2:5]
	v_mfma_f32_16x16x32_bf16 v[2:5], v[176:179], v[228:231], v[2:5]
	s_setprio 0
	s_barrier
	s_add_i32 s22, s22, 2
	s_add_u32 s14, s14, 0x100
	s_addc_u32 s15, s15, 0
	s_cmp_gt_u32 s22, 29
	s_mov_b64 s[16:17], s[18:19]
	s_cbranch_scc0 .LBB0_601
; __device__ __forceinline__ unsigned cvt_pk_bf16(float lo, float hi) { unsigned r; asm volatile("v_cvt_pk_bf16_f32 %0, %1, %2" : "=v"(r) : "v"(lo), "v"(hi)); return r; }
;     __device__ __forceinline__ void operator()(const f32x4 (&acc)[2][2][4][2], const Unit& u, int wr, int wc, int fr, int fq) const {
;         const int row0 = u.pm * BM + wr * 64 + fr; const int col0 = u.pn * BM + wc * 32 + 4 * fq;
; #pragma unroll
;         for (int ai = 0; ai < 2; ++ai) {
;             u32x2 bv[4][2][2];
; #pragma unroll
;             for (int m = 0; m < 4; ++m) { const size_t off = (size_t)(row0 + ai * HALF + m * 16) * ldc + col0;
; #pragma unroll
;                 for (int bj = 0; bj < 2; ++bj)
; #pragma unroll
;                     for (int n = 0; n < 2; ++n) bv[m][bj][n] = *(const u32x2*)(xb + off + bj * HALF + n * 16); }
;             asm volatile("" ::: "memory");
; #pragma unroll
;             for (int m = 0; m < 4; ++m) {
;                 const int row = row0 + ai * HALF + m * 16;
;                 const size_t off = (size_t)row * ldc + col0;
;                 float s = 0.f;
; #pragma unroll
;                 for (int bj = 0; bj < 2; ++bj)
; #pragma unroll
;                     for (int n = 0; n < 2; ++n) {
;                         const size_t c = off + bj * HALF + n * 16;
;                         const u32x2 w0 = bv[m][bj][n];
;                         const f32x4 b = {__uint_as_float(w0.x << 16), __uint_as_float(w0.x & 0xffff0000u), __uint_as_float(w0.y << 16), __uint_as_float(w0.y & 0xffff0000u)};
;                         const f32x4 o = b + acc[ai][bj][m][n];
;                         if (fin) { *(f32x4*)(outf + c) = o; }
;                         else { u32x2 w; w.x = cvt_pk_bf16(o[0], o[1]); w.y = cvt_pk_bf16(o[2], o[3]); *(u32x2*)(xb + c) = w;
;                                s += (o[0] * o[0] + o[1] * o[1]) + (o[2] * o[2] + o[3] * o[3]); }
;                     }
;                 if (!fin) { s += __shfl_xor(s, 16); s += __shfl_xor(s, 32); if (fq == 0) unsafeAtomicAdd(ssq + row, s); }
	v_lshl_or_b32 v148, s2, 8, v188
	v_lshl_add_u32 v152, s4, 8, v186
	v_ashrrev_i32_e32 v149, 31, v148
	v_lshlrev_b64 v[190:191], 1, v[148:149]
	v_ashrrev_i32_e32 v153, 31, v152
	v_lshl_add_u64 v[150:151], s[48:49], 0, v[190:191]
	v_lshlrev_b64 v[154:155], 12, v[152:153]
	v_lshl_add_u64 v[156:157], v[150:151], 0, v[154:155]
	global_load_dwordx2 v[192:193], v[156:157], off
	global_load_dwordx2 v[194:195], v[156:157], off offset:32
	global_load_dwordx2 v[196:197], v[156:157], off offset:256
	global_load_dwordx2 v[198:199], v[156:157], off offset:288
	v_or_b32_e32 v184, 16, v152
	v_ashrrev_i32_e32 v185, 31, v184
	v_lshlrev_b64 v[156:157], 12, v[184:185]
	v_or_b32_e32 v174, 32, v152
	v_lshl_add_u64 v[156:157], v[150:151], 0, v[156:157]
	v_ashrrev_i32_e32 v175, 31, v174
	global_load_dwordx2 v[182:183], v[156:157], off
	global_load_dwordx2 v[180:181], v[156:157], off offset:32
	global_load_dwordx2 v[178:179], v[156:157], off offset:256
	global_load_dwordx2 v[176:177], v[156:157], off offset:288
	v_lshlrev_b64 v[156:157], 12, v[174:175]
	v_or_b32_e32 v158, 48, v152
	v_lshl_add_u64 v[156:157], v[150:151], 0, v[156:157]
	v_ashrrev_i32_e32 v159, 31, v158
	global_load_dwordx2 v[172:173], v[156:157], off
	global_load_dwordx2 v[170:171], v[156:157], off offset:32
	global_load_dwordx2 v[166:167], v[156:157], off offset:256
	global_load_dwordx2 v[162:163], v[156:157], off offset:288
	v_lshlrev_b64 v[156:157], 12, v[158:159]
	v_lshl_add_u64 v[156:157], v[150:151], 0, v[156:157]
	global_load_dwordx2 v[168:169], v[156:157], off
	global_load_dwordx2 v[164:165], v[156:157], off offset:32
	global_load_dwordx2 v[160:161], v[156:157], off offset:256
	s_nop 0
	global_load_dwordx2 v[156:157], v[156:157], off offset:288
	s_waitcnt vmcnt(0)
	v_lshlrev_b32_e32 v200, 16, v192
	v_and_b32_e32 v201, 0xffff0000, v192
	v_lshlrev_b32_e32 v192, 16, v193
	v_and_b32_e32 v193, 0xffff0000, v193
	v_pk_add_f32 v[126:127], v[126:127], v[200:201]
	v_pk_add_f32 v[128:129], v[128:129], v[192:193]
	v_cvt_pk_bf16_f32 v192, v126, v127
	v_mul_f32_e32 v127, v127, v127
	v_lshl_add_u64 v[200:201], s[48:49], 0, v[154:155]
	v_fmac_f32_e32 v127, v126, v126
	v_mul_f32_e32 v126, v129, v129
	v_lshl_add_u64 v[190:191], v[200:201], 0, v[190:191]
	v_fmac_f32_e32 v126, v128, v128
	v_cvt_pk_bf16_f32 v193, v128, v129
	global_store_dwordx2 v[190:191], v[192:193], off
	v_add_f32_e32 v192, v127, v126
	v_lshlrev_b32_e32 v126, 16, v194
	v_and_b32_e32 v127, 0xffff0000, v194
	v_lshlrev_b32_e32 v128, 16, v195
	v_and_b32_e32 v129, 0xffff0000, v195
	v_pk_add_f32 v[122:123], v[122:123], v[126:127]
	v_pk_add_f32 v[124:125], v[124:125], v[128:129]
	v_cvt_pk_bf16_f32 v126, v122, v123
	v_mul_f32_e32 v123, v123, v123
	v_fmac_f32_e32 v123, v122, v122
	v_mul_f32_e32 v122, v125, v125
	v_fmac_f32_e32 v122, v124, v124
	v_add_f32_e32 v122, v123, v122
	v_cvt_pk_bf16_f32 v127, v124, v125
	global_store_dwordx2 v[190:191], v[126:127], off offset:32
	v_add_f32_e32 v126, v192, v122
	v_lshlrev_b32_e32 v122, 16, v196
	v_and_b32_e32 v123, 0xffff0000, v196
	v_lshlrev_b32_e32 v124, 16, v197
	v_and_b32_e32 v125, 0xffff0000, v197
	v_pk_add_f32 v[118:119], v[118:119], v[122:123]
	v_pk_add_f32 v[120:121], v[120:121], v[124:125]
	v_cvt_pk_bf16_f32 v122, v118, v119
	v_mul_f32_e32 v119, v119, v119
	v_fmac_f32_e32 v119, v118, v118
	v_mul_f32_e32 v118, v121, v121
	v_fmac_f32_e32 v118, v120, v120
	v_add_f32_e32 v118, v119, v118
	v_cvt_pk_bf16_f32 v123, v120, v121
	global_store_dwordx2 v[190:191], v[122:123], off offset:256
	v_add_f32_e32 v122, v126, v118
	v_lshlrev_b32_e32 v118, 16, v198
	v_and_b32_e32 v119, 0xffff0000, v198
	v_lshlrev_b32_e32 v120, 16, v199
	v_and_b32_e32 v121, 0xffff0000, v199
	v_pk_add_f32 v[114:115], v[114:115], v[118:119]
	v_pk_add_f32 v[116:117], v[116:117], v[120:121]
	v_cvt_pk_bf16_f32 v118, v114, v115
	v_mul_f32_e32 v115, v115, v115
	v_fmac_f32_e32 v115, v114, v114
	v_mul_f32_e32 v114, v117, v117
	v_cvt_pk_bf16_f32 v119, v116, v117
	v_fmac_f32_e32 v114, v116, v116
	v_and_b32_e32 v116, 64, v208
	v_add_f32_e32 v114, v115, v114
	v_xor_b32_e32 v115, 16, v208
	v_add_u32_e32 v117, 64, v116
	v_cmp_lt_i32_e32 vcc, v115, v117
	v_add_f32_e32 v114, v122, v114
	global_store_dwordx2 v[190:191], v[118:119], off offset:288
	v_cndmask_b32_e32 v115, v208, v115, vcc
	v_lshlrev_b32_e32 v116, 2, v115
	ds_bpermute_b32 v115, v116, v114
	s_waitcnt lgkmcnt(0)
	v_add_f32_e32 v118, v114, v115
	v_xor_b32_e32 v114, 32, v208
	v_cmp_lt_i32_e32 vcc, v114, v117
	s_nop 1
	v_cndmask_b32_e32 v114, v208, v114, vcc
	v_lshlrev_b32_e32 v117, 2, v114
	ds_bpermute_b32 v119, v117, v118
	v_lshl_add_u64 v[114:115], v[152:153], 2, s[50:51]
	s_and_saveexec_b64 s[16:17], s[42:43]
	s_cbranch_execz .LBB0_604
	s_waitcnt lgkmcnt(0)
	v_add_f32_e32 v118, v118, v119
	global_atomic_add_f32 v[114:115], v118, off

; #define PG8_STAGE(bufoff, gbase, voff) do { _Pragma("unroll") for (int _i = 0; _i < 2; ++_i) \
;         __builtin_amdgcn_global_load_lds((const unsigned*)((const char*)(gbase) + (voff)[_i]), (PG8_LAS unsigned*)(lds + (bufoff) + ldsw + _i * 8192), 16, 0, 0); } while (0)
; #define PG8_LDA(dst, b, h) do { _Pragma("unroll") for (int m = 0; m < 4; ++m) _Pragma("unroll") for (int k = 0; k < 2; ++k) dst[m][k] = *(const PG8_LAS bf16x8*)(lds + PG8_SA(b, h) + aoff + m * 2048 + k * 1024); } while (0)
; #define PG8_LDB(dst, b, h) do { _Pragma("unroll") for (int n = 0; n < 2; ++n) _Pragma("unroll") for (int k = 0; k < 2; ++k) dst[n][k] = *(const PG8_LAS bf16x8*)(lds + PG8_SB(b, h) + boff + n * 2048 + k * 1024); } while (0)
; #define PG8_MMA(ai, bj, At, Bt) do { __builtin_amdgcn_s_setprio(1); _Pragma("unroll") for (int m = 0; m < 4; ++m) _Pragma("unroll") for (int n = 0; n < 2; ++n) _Pragma("unroll") for (int k = 0; k < 2; ++k) \
;         acc[ai][bj][m][n] = __builtin_amdgcn_mfma_f32_16x16x32_bf16(Bt[n][k], At[m][k], acc[ai][bj][m][n], 0, 0, 0); __builtin_amdgcn_s_setprio(0); } while (0)
; #define PG8_WAIT_V(n) asm volatile("s_waitcnt vmcnt(" #n ")" ::: "memory")
; #define PG8_WAIT_L(n) asm volatile("s_waitcnt lgkmcnt(" #n ")" ::: "memory")
; template <class Epi, class Sched, bool ALIGN_EPI = false, bool SP2 = false>
; __device__ __forceinline__ void gemm_phase(PG8_LAS unsigned char* lds, const Gemm g, const Sched& S, const Epi& E) {
;     ...
;             const bool last = (t == nt - 2);
;             const char* a1 = cA + (size_t)(t + 1) * kstep;
;             const char* a2 = last ? nA : cA + (size_t)(t + 2) * kstep; const char* b2 = last ? nB : cB + (size_t)(t + 2) * kstep;
;             const char* a3 = a2 + kstep; const char* b3 = b2 + kstep;
;             if (last && has_next) S.a_ready(nxt);
;             if constexpr (SP2) {
;             PG8_LDB(B0, 0, 0); PG8_LDB(B1, 0, 1); PG8_SCHED; PG8_LDA(At, 0, 0); PG8_STAGE(PG8_SA(1, 1), a1 + hstep, voffA);
;             PG8_WAIT_V(8); PG8_WAIT_L(0); PG8_BAR; PG8_MMA(0, 0, At, B0); PG8_MMA(0, 1, At, B1); PG8_BAR; PG8_SCHED;
;             PG8_LDA(At, 0, 1); PG8_STAGE(PG8_SB(0, 0), b2, voffB); PG8_STAGE(PG8_SB(0, 1), b2 + hstep, voffB); PG8_STAGE(PG8_SA(0, 0), a2, voffA);
;             PG8_WAIT_V(8); PG8_WAIT_L(0); PG8_BAR; PG8_MMA(1, 0, At, B0); PG8_MMA(1, 1, At, B1); PG8_BAR; PG8_SCHED;
.LBB0_686:
	s_add_u32 s10, s16, 0xfff80080
	s_addc_u32 s11, s17, -1
	s_add_i32 s12, 0, 0x10000
	s_cmp_eq_u32 s22, 28
	s_cselect_b32 s25, s5, s11
	s_cselect_b32 s24, s7, s10
	v_add_u32_e32 v160, s12, v163
	s_cselect_b32 s19, s8, s15
	s_cselect_b32 s18, s9, s14
	s_add_i32 s13, 0, 0x14000
	ds_read_b128 v[152:155], v160
	ds_read_b128 v[156:159], v160 offset:1024
	ds_read_b128 v[166:169], v160 offset:2048
	ds_read_b128 v[170:173], v160 offset:3072
	v_add_u32_e32 v160, s13, v163
	ds_read_b128 v[174:177], v160
	ds_read_b128 v[178:181], v160 offset:1024
	ds_read_b128 v[182:185], v160 offset:2048
	ds_read_b128 v[186:189], v160 offset:3072
	v_lshl_add_u64 v[160:161], s[16:17], 0, v[148:149]
	s_add_i32 m0, s59, 0xc000
	ds_read_b128 v[190:193], v165
	ds_read_b128 v[194:197], v165 offset:1024
	ds_read_b128 v[198:201], v165 offset:2048
	ds_read_b128 v[216:219], v165 offset:3072
	ds_read_b128 v[220:223], v165 offset:4096
	ds_read_b128 v[224:227], v165 offset:5120
	ds_read_b128 v[228:231], v165 offset:6144
	ds_read_b128 v[232:235], v165 offset:7168
	global_load_lds_dwordx4 v[160:161], off
	v_lshl_add_u64 v[160:161], s[16:17], 0, v[150:151]
	s_add_i32 m0, s59, 0xe000
	s_nop 0
	global_load_lds_dwordx4 v[160:161], off
	s_waitcnt vmcnt(8)
	s_waitcnt lgkmcnt(0)
	s_barrier
	s_setprio 1
	s_waitcnt lgkmcnt(0)
	v_mfma_f32_16x16x32_bf16 v[126:129], v[152:155], v[190:193], v[126:129]
	v_mfma_f32_16x16x32_bf16 v[126:129], v[156:159], v[194:197], v[126:129]
	v_mfma_f32_16x16x32_bf16 v[122:125], v[166:169], v[190:193], v[122:125]
	v_mfma_f32_16x16x32_bf16 v[122:125], v[170:173], v[194:197], v[122:125]
	v_mfma_f32_16x16x32_bf16 v[110:113], v[152:155], v[198:201], v[110:113]
	v_mfma_f32_16x16x32_bf16 v[110:113], v[156:159], v[216:219], v[110:113]
	v_mfma_f32_16x16x32_bf16 v[106:109], v[166:169], v[198:201], v[106:109]
	v_mfma_f32_16x16x32_bf16 v[106:109], v[170:173], v[216:219], v[106:109]
	v_mfma_f32_16x16x32_bf16 v[94:97], v[152:155], v[220:223], v[94:97]
	v_mfma_f32_16x16x32_bf16 v[94:97], v[156:159], v[224:227], v[94:97]
	v_mfma_f32_16x16x32_bf16 v[90:93], v[166:169], v[220:223], v[90:93]
	v_mfma_f32_16x16x32_bf16 v[90:93], v[170:173], v[224:227], v[90:93]
	v_mfma_f32_16x16x32_bf16 v[78:81], v[152:155], v[228:231], v[78:81]
	v_mfma_f32_16x16x32_bf16 v[78:81], v[156:159], v[232:235], v[78:81]
	v_mfma_f32_16x16x32_bf16 v[74:77], v[166:169], v[228:231], v[74:77]
	v_mfma_f32_16x16x32_bf16 v[74:77], v[170:173], v[232:235], v[74:77]
	s_setprio 0
	s_setprio 1
	v_mfma_f32_16x16x32_bf16 v[118:121], v[174:177], v[190:193], v[118:121]
	v_mfma_f32_16x16x32_bf16 v[118:121], v[178:181], v[194:197], v[118:121]
	v_mfma_f32_16x16x32_bf16 v[114:117], v[182:185], v[190:193], v[114:117]
	v_mfma_f32_16x16x32_bf16 v[114:117], v[186:189], v[194:197], v[114:117]
	v_mfma_f32_16x16x32_bf16 v[102:105], v[174:177], v[198:201], v[102:105]
	v_mfma_f32_16x16x32_bf16 v[102:105], v[178:181], v[216:219], v[102:105]
	v_mfma_f32_16x16x32_bf16 v[98:101], v[182:185], v[198:201], v[98:101]
	v_mfma_f32_16x16x32_bf16 v[98:101], v[186:189], v[216:219], v[98:101]
	v_mfma_f32_16x16x32_bf16 v[86:89], v[174:177], v[220:223], v[86:89]
	v_mfma_f32_16x16x32_bf16 v[86:89], v[178:181], v[224:227], v[86:89]
	v_mfma_f32_16x16x32_bf16 v[82:85], v[182:185], v[220:223], v[82:85]
	v_mfma_f32_16x16x32_bf16 v[82:85], v[186:189], v[224:227], v[82:85]
	v_mfma_f32_16x16x32_bf16 v[70:73], v[174:177], v[228:231], v[70:73]
	v_mfma_f32_16x16x32_bf16 v[70:73], v[178:181], v[232:235], v[70:73]
	v_mfma_f32_16x16x32_bf16 v[66:69], v[182:185], v[228:231], v[66:69]
	v_mfma_f32_16x16x32_bf16 v[66:69], v[186:189], v[232:235], v[66:69]
	s_setprio 0
	s_barrier
	s_add_i32 s10, s12, s58
	v_lshl_add_u64 v[160:161], s[18:19], 0, v[0:1]
	s_mov_b32 m0, s10
	ds_read_b128 v[190:193], v165 offset:16384
	ds_read_b128 v[194:197], v165 offset:17408
	ds_read_b128 v[198:201], v165 offset:18432
	ds_read_b128 v[216:219], v165 offset:19456
	ds_read_b128 v[220:223], v165 offset:20480
	ds_read_b128 v[224:227], v165 offset:21504
	ds_read_b128 v[228:231], v165 offset:22528
	ds_read_b128 v[232:235], v165 offset:23552
	global_load_lds_dwordx4 v[160:161], off
	s_add_i32 m0, s10, 0x2000
	s_add_u32 s10, s18, 0x80000
	v_lshl_add_u64 v[236:237], s[18:19], 0, v[142:143]
	s_addc_u32 s11, s19, 0
	s_add_i32 s12, s13, s58
	global_load_lds_dwordx4 v[236:237], off
	v_lshl_add_u64 v[238:239], s[10:11], 0, v[0:1]
	s_mov_b32 m0, s12
	v_lshl_add_u64 v[240:241], s[24:25], 0, v[144:145]
	global_load_lds_dwordx4 v[238:239], off
	v_lshl_add_u64 v[238:239], s[10:11], 0, v[142:143]
	s_add_i32 m0, s12, 0x2000
	s_nop 0
	global_load_lds_dwordx4 v[238:239], off
	v_lshl_add_u64 v[238:239], s[24:25], 0, v[146:147]
	s_mov_b32 m0, s59
	s_nop 0
	global_load_lds_dwordx4 v[238:239], off
	s_mov_b32 m0, s60
	s_nop 0
	global_load_lds_dwordx4 v[240:241], off
	s_waitcnt vmcnt(8)
	s_waitcnt lgkmcnt(0)
	s_barrier
; #define PG8_STAGE(bufoff, gbase, voff) do { _Pragma("unroll") for (int _i = 0; _i < 2; ++_i) \
;         __builtin_amdgcn_global_load_lds((const unsigned*)((const char*)(gbase) + (voff)[_i]), (PG8_LAS unsigned*)(lds + (bufoff) + ldsw + _i * 8192), 16, 0, 0); } while (0)
; #define PG8_LDA(dst, b, h) do { _Pragma("unroll") for (int m = 0; m < 4; ++m) _Pragma("unroll") for (int k = 0; k < 2; ++k) dst[m][k] = *(const PG8_LAS bf16x8*)(lds + PG8_SA(b, h) + aoff + m * 2048 + k * 1024); } while (0)
; #define PG8_LDB(dst, b, h) do { _Pragma("unroll") for (int n = 0; n < 2; ++n) _Pragma("unroll") for (int k = 0; k < 2; ++k) dst[n][k] = *(const PG8_LAS bf16x8*)(lds + PG8_SB(b, h) + boff + n * 2048 + k * 1024); } while (0)
; #define PG8_MMA(ai, bj, At, Bt) do { __builtin_amdgcn_s_setprio(1); _Pragma("unroll") for (int m = 0; m < 4; ++m) _Pragma("unroll") for (int n = 0; n < 2; ++n) _Pragma("unroll") for (int k = 0; k < 2; ++k) \
;         acc[ai][bj][m][n] = __builtin_amdgcn_mfma_f32_16x16x32_bf16(Bt[n][k], At[m][k], acc[ai][bj][m][n], 0, 0, 0); __builtin_amdgcn_s_setprio(0); } while (0)
; #define PG8_WAIT_V(n) asm volatile("s_waitcnt vmcnt(" #n ")" ::: "memory")
; #define PG8_WAIT_L(n) asm volatile("s_waitcnt lgkmcnt(" #n ")" ::: "memory")
; #define PG8_BAR __builtin_amdgcn_s_barrier()
; #define PG8_SCHED __builtin_amdgcn_sched_barrier(0)
; template <class Epi, class Sched, bool ALIGN_EPI = false, bool SP2 = false>
; __device__ __forceinline__ void gemm_phase(PG8_LAS unsigned char* lds, const Gemm g, const Sched& S, const Epi& E) {
;     ...
;             PG8_WAIT_V(8); PG8_WAIT_L(0); PG8_BAR; PG8_MMA(1, 0, At, B0); PG8_MMA(1, 1, At, B1); PG8_BAR; PG8_SCHED;
;             PG8_LDB(B0, 1, 0); PG8_LDB(B1, 1, 1); PG8_SCHED; PG8_LDA(At, 1, 0); PG8_STAGE(PG8_SA(0, 1), a2 + hstep, voffA);
;             PG8_WAIT_V(8); PG8_WAIT_L(0); PG8_BAR; PG8_MMA(0, 0, At, B0); PG8_MMA(0, 1, At, B1); PG8_BAR; PG8_SCHED;
	s_setprio 1
	s_waitcnt lgkmcnt(0)
	v_mfma_f32_16x16x32_bf16 v[62:65], v[152:155], v[190:193], v[62:65]
	v_mfma_f32_16x16x32_bf16 v[62:65], v[156:159], v[194:197], v[62:65]
	v_mfma_f32_16x16x32_bf16 v[58:61], v[166:169], v[190:193], v[58:61]
	v_mfma_f32_16x16x32_bf16 v[58:61], v[170:173], v[194:197], v[58:61]
	v_mfma_f32_16x16x32_bf16 v[46:49], v[152:155], v[198:201], v[46:49]
	v_mfma_f32_16x16x32_bf16 v[46:49], v[156:159], v[216:219], v[46:49]
	v_mfma_f32_16x16x32_bf16 v[42:45], v[166:169], v[198:201], v[42:45]
	v_mfma_f32_16x16x32_bf16 v[42:45], v[170:173], v[216:219], v[42:45]
	v_mfma_f32_16x16x32_bf16 v[30:33], v[152:155], v[220:223], v[30:33]
	v_mfma_f32_16x16x32_bf16 v[30:33], v[156:159], v[224:227], v[30:33]
	v_mfma_f32_16x16x32_bf16 v[26:29], v[166:169], v[220:223], v[26:29]
	v_mfma_f32_16x16x32_bf16 v[26:29], v[170:173], v[224:227], v[26:29]
	v_mfma_f32_16x16x32_bf16 v[14:17], v[152:155], v[228:231], v[14:17]
	v_mfma_f32_16x16x32_bf16 v[14:17], v[156:159], v[232:235], v[14:17]
	v_mfma_f32_16x16x32_bf16 v[10:13], v[166:169], v[228:231], v[10:13]
	v_mfma_f32_16x16x32_bf16 v[10:13], v[170:173], v[232:235], v[10:13]
	s_setprio 0
	s_setprio 1
	v_mfma_f32_16x16x32_bf16 v[54:57], v[174:177], v[190:193], v[54:57]
	v_mfma_f32_16x16x32_bf16 v[54:57], v[178:181], v[194:197], v[54:57]
	v_mfma_f32_16x16x32_bf16 v[50:53], v[182:185], v[190:193], v[50:53]
	v_mfma_f32_16x16x32_bf16 v[50:53], v[186:189], v[194:197], v[50:53]
	v_mfma_f32_16x16x32_bf16 v[38:41], v[174:177], v[198:201], v[38:41]
	v_mfma_f32_16x16x32_bf16 v[38:41], v[178:181], v[216:219], v[38:41]
	v_mfma_f32_16x16x32_bf16 v[34:37], v[182:185], v[198:201], v[34:37]
	v_mfma_f32_16x16x32_bf16 v[34:37], v[186:189], v[216:219], v[34:37]
	v_mfma_f32_16x16x32_bf16 v[22:25], v[174:177], v[220:223], v[22:25]
	v_mfma_f32_16x16x32_bf16 v[22:25], v[178:181], v[224:227], v[22:25]
	v_mfma_f32_16x16x32_bf16 v[18:21], v[182:185], v[220:223], v[18:21]
	v_mfma_f32_16x16x32_bf16 v[18:21], v[186:189], v[224:227], v[18:21]
	v_mfma_f32_16x16x32_bf16 v[6:9], v[174:177], v[228:231], v[6:9]
	v_mfma_f32_16x16x32_bf16 v[6:9], v[178:181], v[232:235], v[6:9]
	v_mfma_f32_16x16x32_bf16 v[2:5], v[182:185], v[228:231], v[2:5]
	v_mfma_f32_16x16x32_bf16 v[2:5], v[186:189], v[232:235], v[2:5]
	s_setprio 0
	s_barrier
	s_add_i32 s12, 0, 0x18000
	s_add_i32 s13, 0, 0x1c000
	v_add_u32_e32 v170, s12, v163
	v_add_u32_e32 v186, s13, v163
	ds_read_b128 v[152:155], v170
	ds_read_b128 v[156:159], v170 offset:1024
	ds_read_b128 v[166:169], v170 offset:2048
	ds_read_b128 v[170:173], v170 offset:3072
	ds_read_b128 v[174:177], v186
	ds_read_b128 v[178:181], v186 offset:1024
	ds_read_b128 v[182:185], v186 offset:2048
	ds_read_b128 v[186:189], v186 offset:3072
	s_add_u32 s10, s24, 0x80000
	s_addc_u32 s11, s25, 0
	s_mov_b32 m0, s61
	v_lshl_add_u64 v[242:243], s[10:11], 0, v[146:147]
	ds_read_b128 v[190:193], v165 offset:32768
	ds_read_b128 v[194:197], v165 offset:33792
	ds_read_b128 v[198:201], v165 offset:34816
	ds_read_b128 v[216:219], v165 offset:35840
	ds_read_b128 v[220:223], v165 offset:36864
	ds_read_b128 v[224:227], v165 offset:37888
	ds_read_b128 v[228:231], v165 offset:38912
	ds_read_b128 v[232:235], v165 offset:39936
	global_load_lds_dwordx4 v[242:243], off
	v_lshl_add_u64 v[242:243], s[10:11], 0, v[144:145]
	s_mov_b32 m0, s62
	s_nop 0
	global_load_lds_dwordx4 v[242:243], off
	s_waitcnt vmcnt(8)
	s_waitcnt lgkmcnt(0)
	s_barrier
	s_setprio 1
	s_waitcnt lgkmcnt(0)
	v_mfma_f32_16x16x32_bf16 v[126:129], v[152:155], v[190:193], v[126:129]
	v_mfma_f32_16x16x32_bf16 v[126:129], v[156:159], v[194:197], v[126:129]
	v_mfma_f32_16x16x32_bf16 v[122:125], v[166:169], v[190:193], v[122:125]
	v_mfma_f32_16x16x32_bf16 v[122:125], v[170:173], v[194:197], v[122:125]
	v_mfma_f32_16x16x32_bf16 v[110:113], v[152:155], v[198:201], v[110:113]
	v_mfma_f32_16x16x32_bf16 v[110:113], v[156:159], v[216:219], v[110:113]
	v_mfma_f32_16x16x32_bf16 v[106:109], v[166:169], v[198:201], v[106:109]
	v_mfma_f32_16x16x32_bf16 v[106:109], v[170:173], v[216:219], v[106:109]
	v_mfma_f32_16x16x32_bf16 v[94:97], v[152:155], v[220:223], v[94:97]
	v_mfma_f32_16x16x32_bf16 v[94:97], v[156:159], v[224:227], v[94:97]
	v_mfma_f32_16x16x32_bf16 v[90:93], v[166:169], v[220:223], v[90:93]
	v_mfma_f32_16x16x32_bf16 v[90:93], v[170:173], v[224:227], v[90:93]
	v_mfma_f32_16x16x32_bf16 v[78:81], v[152:155], v[228:231], v[78:81]
	v_mfma_f32_16x16x32_bf16 v[78:81], v[156:159], v[232:235], v[78:81]
	v_mfma_f32_16x16x32_bf16 v[74:77], v[166:169], v[228:231], v[74:77]
	v_mfma_f32_16x16x32_bf16 v[74:77], v[170:173], v[232:235], v[74:77]
	s_setprio 0
	s_setprio 1
	v_mfma_f32_16x16x32_bf16 v[118:121], v[174:177], v[190:193], v[118:121]
	v_mfma_f32_16x16x32_bf16 v[118:121], v[178:181], v[194:197], v[118:121]
	v_mfma_f32_16x16x32_bf16 v[114:117], v[182:185], v[190:193], v[114:117]
	v_mfma_f32_16x16x32_bf16 v[114:117], v[186:189], v[194:197], v[114:117]
	v_mfma_f32_16x16x32_bf16 v[102:105], v[174:177], v[198:201], v[102:105]
	v_mfma_f32_16x16x32_bf16 v[102:105], v[178:181], v[216:219], v[102:105]
	v_mfma_f32_16x16x32_bf16 v[98:101], v[182:185], v[198:201], v[98:101]
	v_mfma_f32_16x16x32_bf16 v[98:101], v[186:189], v[216:219], v[98:101]
	v_mfma_f32_16x16x32_bf16 v[86:89], v[174:177], v[220:223], v[86:89]
	v_mfma_f32_16x16x32_bf16 v[86:89], v[178:181], v[224:227], v[86:89]
	v_mfma_f32_16x16x32_bf16 v[82:85], v[182:185], v[220:223], v[82:85]
	v_mfma_f32_16x16x32_bf16 v[82:85], v[186:189], v[224:227], v[82:85]
	v_mfma_f32_16x16x32_bf16 v[70:73], v[174:177], v[228:231], v[70:73]
	v_mfma_f32_16x16x32_bf16 v[70:73], v[178:181], v[232:235], v[70:73]
	v_mfma_f32_16x16x32_bf16 v[66:69], v[182:185], v[228:231], v[66:69]
	v_mfma_f32_16x16x32_bf16 v[66:69], v[186:189], v[232:235], v[66:69]
	s_setprio 0
	s_barrier
; #define PG8_STAGE(bufoff, gbase, voff) do { _Pragma("unroll") for (int _i = 0; _i < 2; ++_i) \
;         __builtin_amdgcn_global_load_lds((const unsigned*)((const char*)(gbase) + (voff)[_i]), (PG8_LAS unsigned*)(lds + (bufoff) + ldsw + _i * 8192), 16, 0, 0); } while (0)
; #define PG8_LDA(dst, b, h) do { _Pragma("unroll") for (int m = 0; m < 4; ++m) _Pragma("unroll") for (int k = 0; k < 2; ++k) dst[m][k] = *(const PG8_LAS bf16x8*)(lds + PG8_SA(b, h) + aoff + m * 2048 + k * 1024); } while (0)
; #define PG8_MMA(ai, bj, At, Bt) do { __builtin_amdgcn_s_setprio(1); _Pragma("unroll") for (int m = 0; m < 4; ++m) _Pragma("unroll") for (int n = 0; n < 2; ++n) _Pragma("unroll") for (int k = 0; k < 2; ++k) \
;         acc[ai][bj][m][n] = __builtin_amdgcn_mfma_f32_16x16x32_bf16(Bt[n][k], At[m][k], acc[ai][bj][m][n], 0, 0, 0); __builtin_amdgcn_s_setprio(0); } while (0)
; #define PG8_WAIT_V(n) asm volatile("s_waitcnt vmcnt(" #n ")" ::: "memory")
; #define PG8_WAIT_L(n) asm volatile("s_waitcnt lgkmcnt(" #n ")" ::: "memory")
; #define PG8_BAR __builtin_amdgcn_s_barrier()
; #define PG8_SCHED __builtin_amdgcn_sched_barrier(0)
; template <class Epi, class Sched, bool ALIGN_EPI = false, bool SP2 = false>
; __device__ __forceinline__ void gemm_phase(PG8_LAS unsigned char* lds, const Gemm g, const Sched& S, const Epi& E) {
;     ...
;             PG8_LDA(At, 1, 1); PG8_STAGE(PG8_SB(1, 0), b3, voffB); PG8_STAGE(PG8_SB(1, 1), b3 + hstep, voffB); PG8_STAGE(PG8_SA(1, 0), a3, voffA);
;             PG8_WAIT_V(8); PG8_WAIT_L(0); PG8_BAR; PG8_MMA(1, 0, At, B0); PG8_MMA(1, 1, At, B1); PG8_BAR; PG8_SCHED;
;     ...
;         if constexpr (ALIGN_EPI) { if (wr == 0) PG8_BAR; }
	s_add_i32 s10, s12, s58
	v_lshl_add_u64 v[160:161], v[160:161], 0, s[30:31]
	s_mov_b32 m0, s10
	ds_read_b128 v[190:193], v165 offset:49152
	ds_read_b128 v[194:197], v165 offset:50176
	ds_read_b128 v[198:201], v165 offset:51200
	ds_read_b128 v[216:219], v165 offset:52224
	ds_read_b128 v[220:223], v165 offset:53248
	ds_read_b128 v[224:227], v165 offset:54272
	ds_read_b128 v[228:231], v165 offset:55296
	ds_read_b128 v[232:235], v165 offset:56320
	global_load_lds_dwordx4 v[160:161], off
	s_add_i32 m0, s10, 0x2000
	s_add_u32 s10, s18, 0x80080
	v_lshl_add_u64 v[160:161], v[236:237], 0, s[30:31]
	s_addc_u32 s11, s19, 0
	s_add_i32 s12, s13, s58
	global_load_lds_dwordx4 v[160:161], off
	v_lshl_add_u64 v[160:161], s[10:11], 0, v[0:1]
	s_mov_b32 m0, s12
	s_nop 0
	global_load_lds_dwordx4 v[160:161], off
	v_lshl_add_u64 v[160:161], s[10:11], 0, v[142:143]
	s_add_i32 m0, s12, 0x2000
	s_nop 0
	global_load_lds_dwordx4 v[160:161], off
	v_lshl_add_u64 v[160:161], v[238:239], 0, s[30:31]
	s_mov_b32 m0, s63
	s_nop 0
	global_load_lds_dwordx4 v[160:161], off
	v_lshl_add_u64 v[160:161], v[240:241], 0, s[30:31]
	s_mov_b32 m0, s64
	s_nop 0
	global_load_lds_dwordx4 v[160:161], off
	s_waitcnt vmcnt(8)
	s_waitcnt lgkmcnt(0)
	s_barrier
	s_setprio 1
	s_waitcnt lgkmcnt(0)
	v_mfma_f32_16x16x32_bf16 v[62:65], v[152:155], v[190:193], v[62:65]
	v_mfma_f32_16x16x32_bf16 v[62:65], v[156:159], v[194:197], v[62:65]
	v_mfma_f32_16x16x32_bf16 v[58:61], v[166:169], v[190:193], v[58:61]
	v_mfma_f32_16x16x32_bf16 v[58:61], v[170:173], v[194:197], v[58:61]
	v_mfma_f32_16x16x32_bf16 v[46:49], v[152:155], v[198:201], v[46:49]
	v_mfma_f32_16x16x32_bf16 v[46:49], v[156:159], v[216:219], v[46:49]
	v_mfma_f32_16x16x32_bf16 v[42:45], v[166:169], v[198:201], v[42:45]
	v_mfma_f32_16x16x32_bf16 v[42:45], v[170:173], v[216:219], v[42:45]
	v_mfma_f32_16x16x32_bf16 v[30:33], v[152:155], v[220:223], v[30:33]
	v_mfma_f32_16x16x32_bf16 v[30:33], v[156:159], v[224:227], v[30:33]
	v_mfma_f32_16x16x32_bf16 v[26:29], v[166:169], v[220:223], v[26:29]
	v_mfma_f32_16x16x32_bf16 v[26:29], v[170:173], v[224:227], v[26:29]
	v_mfma_f32_16x16x32_bf16 v[14:17], v[152:155], v[228:231], v[14:17]
	v_mfma_f32_16x16x32_bf16 v[14:17], v[156:159], v[232:235], v[14:17]
	v_mfma_f32_16x16x32_bf16 v[10:13], v[166:169], v[228:231], v[10:13]
	v_mfma_f32_16x16x32_bf16 v[10:13], v[170:173], v[232:235], v[10:13]
	s_setprio 0
	s_setprio 1
	v_mfma_f32_16x16x32_bf16 v[54:57], v[174:177], v[190:193], v[54:57]
	v_mfma_f32_16x16x32_bf16 v[54:57], v[178:181], v[194:197], v[54:57]
	v_mfma_f32_16x16x32_bf16 v[50:53], v[182:185], v[190:193], v[50:53]
	v_mfma_f32_16x16x32_bf16 v[50:53], v[186:189], v[194:197], v[50:53]
	v_mfma_f32_16x16x32_bf16 v[38:41], v[174:177], v[198:201], v[38:41]
	v_mfma_f32_16x16x32_bf16 v[38:41], v[178:181], v[216:219], v[38:41]
	v_mfma_f32_16x16x32_bf16 v[34:37], v[182:185], v[198:201], v[34:37]
	v_mfma_f32_16x16x32_bf16 v[34:37], v[186:189], v[216:219], v[34:37]
	v_mfma_f32_16x16x32_bf16 v[22:25], v[174:177], v[220:223], v[22:25]
	v_mfma_f32_16x16x32_bf16 v[22:25], v[178:181], v[224:227], v[22:25]
	v_mfma_f32_16x16x32_bf16 v[18:21], v[182:185], v[220:223], v[18:21]
	v_mfma_f32_16x16x32_bf16 v[18:21], v[186:189], v[224:227], v[18:21]
	v_mfma_f32_16x16x32_bf16 v[6:9], v[174:177], v[228:231], v[6:9]
	v_mfma_f32_16x16x32_bf16 v[6:9], v[178:181], v[232:235], v[6:9]
	v_mfma_f32_16x16x32_bf16 v[2:5], v[182:185], v[228:231], v[2:5]
	v_mfma_f32_16x16x32_bf16 v[2:5], v[186:189], v[232:235], v[2:5]
	s_setprio 0
	s_barrier
	s_add_i32 s22, s22, 2
	s_add_u32 s16, s16, 0x100
	s_addc_u32 s17, s17, 0
	s_add_u32 s14, s14, 0x100
	s_addc_u32 s15, s15, 0
	s_cmp_gt_u32 s22, 29
	s_cbranch_scc0 .LBB0_686
	s_and_b64 vcc, exec, s[50:51]
	s_cbranch_vccz .LBB0_689
	s_barrier

; #define PG8_STAGE(bufoff, gbase, voff) do { _Pragma("unroll") for (int _i = 0; _i < 2; ++_i) \
;         __builtin_amdgcn_global_load_lds((const unsigned*)((const char*)(gbase) + (voff)[_i]), (PG8_LAS unsigned*)(lds + (bufoff) + ldsw + _i * 8192), 16, 0, 0); } while (0)
; #define PG8_LDA(dst, b, h) do { _Pragma("unroll") for (int m = 0; m < 4; ++m) _Pragma("unroll") for (int k = 0; k < 2; ++k) dst[m][k] = *(const PG8_LAS bf16x8*)(lds + PG8_SA(b, h) + aoff + m * 2048 + k * 1024); } while (0)
; #define PG8_LDB(dst, b, h) do { _Pragma("unroll") for (int n = 0; n < 2; ++n) _Pragma("unroll") for (int k = 0; k < 2; ++k) dst[n][k] = *(const PG8_LAS bf16x8*)(lds + PG8_SB(b, h) + boff + n * 2048 + k * 1024); } while (0)
; #define PG8_MMA(ai, bj, At, Bt) do { __builtin_amdgcn_s_setprio(1); _Pragma("unroll") for (int m = 0; m < 4; ++m) _Pragma("unroll") for (int n = 0; n < 2; ++n) _Pragma("unroll") for (int k = 0; k < 2; ++k) \
;         acc[ai][bj][m][n] = __builtin_amdgcn_mfma_f32_16x16x32_bf16(Bt[n][k], At[m][k], acc[ai][bj][m][n], 0, 0, 0); __builtin_amdgcn_s_setprio(0); } while (0)
; #define PG8_WAIT_V(n) asm volatile("s_waitcnt vmcnt(" #n ")" ::: "memory")
; #define PG8_WAIT_L(n) asm volatile("s_waitcnt lgkmcnt(" #n ")" ::: "memory")
; template <class Epi, class Sched, bool ALIGN_EPI = false, bool SP2 = false>
; __device__ __forceinline__ void gemm_phase(PG8_LAS unsigned char* lds, const Gemm g, const Sched& S, const Epi& E) {
;     ...
;             const bool last = (t == nt - 2);
;             const char* a1 = cA + (size_t)(t + 1) * kstep;
;             const char* a2 = last ? nA : cA + (size_t)(t + 2) * kstep; const char* b2 = last ? nB : cB + (size_t)(t + 2) * kstep;
;             const char* a3 = a2 + kstep; const char* b3 = b2 + kstep;
;             if (last && has_next) S.a_ready(nxt);
;             if constexpr (SP2) {
;             PG8_LDB(B0, 0, 0); PG8_LDB(B1, 0, 1); PG8_SCHED; PG8_LDA(At, 0, 0); PG8_STAGE(PG8_SA(1, 1), a1 + hstep, voffA);
;             PG8_WAIT_V(8); PG8_WAIT_L(0); PG8_BAR; PG8_MMA(0, 0, At, B0); PG8_MMA(0, 1, At, B1); PG8_BAR; PG8_SCHED;
;             PG8_LDA(At, 0, 1); PG8_STAGE(PG8_SB(0, 0), b2, voffB); PG8_STAGE(PG8_SB(0, 1), b2 + hstep, voffB); PG8_STAGE(PG8_SA(0, 0), a2, voffA);
;             PG8_WAIT_V(8); PG8_WAIT_L(0); PG8_BAR; PG8_MMA(1, 0, At, B0); PG8_MMA(1, 1, At, B1); PG8_BAR; PG8_SCHED;
.LBB0_758:
	s_add_u32 s18, s16, 0x100
	s_addc_u32 s19, s17, 0
	s_add_i32 s10, 0, 0x10000
	s_cmpk_eq_i32 s22, 0x7c
	s_cselect_b32 s27, s5, s19
	s_cselect_b32 s26, s7, s18
	s_cselect_b32 s25, s8, s15
	s_cselect_b32 s24, s9, s14
	s_add_i32 s12, 0, 0x14000
	v_add_u32_e32 v160, s10, v216
	v_add_u32_e32 v176, s12, v216
	ds_read_b128 v[148:151], v160
	ds_read_b128 v[152:155], v160 offset:1024
	ds_read_b128 v[156:159], v160 offset:2048
	ds_read_b128 v[160:163], v160 offset:3072
	ds_read_b128 v[164:167], v176
	ds_read_b128 v[168:171], v176 offset:1024
	ds_read_b128 v[172:175], v176 offset:2048
	ds_read_b128 v[176:179], v176 offset:3072
	v_lshl_add_u64 v[200:201], s[16:17], 0, v[144:145]
	s_add_i32 m0, s64, 0xc000
	ds_read_b128 v[180:183], v218
	ds_read_b128 v[184:187], v218 offset:1024
	ds_read_b128 v[188:191], v218 offset:2048
	ds_read_b128 v[192:195], v218 offset:3072
	ds_read_b128 v[196:199], v218 offset:4096
	ds_read_b128 v[220:223], v218 offset:5120
	ds_read_b128 v[224:227], v218 offset:6144
	ds_read_b128 v[228:231], v218 offset:7168
	global_load_lds_dwordx4 v[200:201], off
	v_lshl_add_u64 v[200:201], s[16:17], 0, v[146:147]
	s_add_i32 m0, s64, 0xe000
	s_nop 0
	global_load_lds_dwordx4 v[200:201], off
	s_waitcnt vmcnt(8)
	s_waitcnt lgkmcnt(0)
	s_barrier
	s_setprio 1
	s_waitcnt lgkmcnt(0)
	v_mfma_f32_16x16x32_bf16 v[126:129], v[148:151], v[180:183], v[126:129]
	v_mfma_f32_16x16x32_bf16 v[126:129], v[152:155], v[184:187], v[126:129]
	v_mfma_f32_16x16x32_bf16 v[122:125], v[156:159], v[180:183], v[122:125]
	v_mfma_f32_16x16x32_bf16 v[122:125], v[160:163], v[184:187], v[122:125]
	v_mfma_f32_16x16x32_bf16 v[110:113], v[148:151], v[188:191], v[110:113]
	v_mfma_f32_16x16x32_bf16 v[110:113], v[152:155], v[192:195], v[110:113]
	v_mfma_f32_16x16x32_bf16 v[106:109], v[156:159], v[188:191], v[106:109]
	v_mfma_f32_16x16x32_bf16 v[106:109], v[160:163], v[192:195], v[106:109]
	v_mfma_f32_16x16x32_bf16 v[94:97], v[148:151], v[196:199], v[94:97]
	v_mfma_f32_16x16x32_bf16 v[94:97], v[152:155], v[220:223], v[94:97]
	v_mfma_f32_16x16x32_bf16 v[90:93], v[156:159], v[196:199], v[90:93]
	v_mfma_f32_16x16x32_bf16 v[90:93], v[160:163], v[220:223], v[90:93]
	v_mfma_f32_16x16x32_bf16 v[78:81], v[148:151], v[224:227], v[78:81]
	v_mfma_f32_16x16x32_bf16 v[78:81], v[152:155], v[228:231], v[78:81]
	v_mfma_f32_16x16x32_bf16 v[74:77], v[156:159], v[224:227], v[74:77]
	v_mfma_f32_16x16x32_bf16 v[74:77], v[160:163], v[228:231], v[74:77]
	s_setprio 0
	s_setprio 1
	v_mfma_f32_16x16x32_bf16 v[118:121], v[164:167], v[180:183], v[118:121]
	v_mfma_f32_16x16x32_bf16 v[118:121], v[168:171], v[184:187], v[118:121]
	v_mfma_f32_16x16x32_bf16 v[114:117], v[172:175], v[180:183], v[114:117]
	v_mfma_f32_16x16x32_bf16 v[114:117], v[176:179], v[184:187], v[114:117]
	v_mfma_f32_16x16x32_bf16 v[102:105], v[164:167], v[188:191], v[102:105]
	v_mfma_f32_16x16x32_bf16 v[102:105], v[168:171], v[192:195], v[102:105]
	v_mfma_f32_16x16x32_bf16 v[98:101], v[172:175], v[188:191], v[98:101]
	v_mfma_f32_16x16x32_bf16 v[98:101], v[176:179], v[192:195], v[98:101]
	v_mfma_f32_16x16x32_bf16 v[86:89], v[164:167], v[196:199], v[86:89]
	v_mfma_f32_16x16x32_bf16 v[86:89], v[168:171], v[220:223], v[86:89]
	v_mfma_f32_16x16x32_bf16 v[82:85], v[172:175], v[196:199], v[82:85]
	v_mfma_f32_16x16x32_bf16 v[82:85], v[176:179], v[220:223], v[82:85]
	v_mfma_f32_16x16x32_bf16 v[70:73], v[164:167], v[224:227], v[70:73]
	v_mfma_f32_16x16x32_bf16 v[70:73], v[168:171], v[228:231], v[70:73]
	v_mfma_f32_16x16x32_bf16 v[66:69], v[172:175], v[224:227], v[66:69]
	v_mfma_f32_16x16x32_bf16 v[66:69], v[176:179], v[228:231], v[66:69]
	s_setprio 0
	s_barrier
	s_add_i32 s10, s10, s63
	v_lshl_add_u64 v[200:201], s[24:25], 0, v[0:1]
	s_mov_b32 m0, s10
	ds_read_b128 v[180:183], v218 offset:16384
	ds_read_b128 v[184:187], v218 offset:17408
	ds_read_b128 v[188:191], v218 offset:18432
	ds_read_b128 v[192:195], v218 offset:19456
	ds_read_b128 v[196:199], v218 offset:20480
	ds_read_b128 v[220:223], v218 offset:21504
	ds_read_b128 v[224:227], v218 offset:22528
	ds_read_b128 v[228:231], v218 offset:23552
	global_load_lds_dwordx4 v[200:201], off
	s_add_i32 m0, s10, 0x2000
	s_add_u32 s10, s24, 0x200000
	v_lshl_add_u64 v[232:233], s[24:25], 0, v[142:143]
	s_addc_u32 s11, s25, 0
	s_add_i32 s12, s12, s63
	global_load_lds_dwordx4 v[232:233], off
	v_lshl_add_u64 v[234:235], s[10:11], 0, v[0:1]
	s_mov_b32 m0, s12
	v_lshl_add_u64 v[236:237], s[26:27], 0, v[142:143]
	global_load_lds_dwordx4 v[234:235], off
	v_lshl_add_u64 v[234:235], s[10:11], 0, v[142:143]
	s_add_i32 m0, s12, 0x2000
	s_nop 0
	global_load_lds_dwordx4 v[234:235], off
	v_lshl_add_u64 v[234:235], s[26:27], 0, v[0:1]
	s_mov_b32 m0, s64
	s_nop 0
	global_load_lds_dwordx4 v[234:235], off
	s_mov_b32 m0, s65
	s_nop 0
	global_load_lds_dwordx4 v[236:237], off
	s_waitcnt vmcnt(8)
	s_waitcnt lgkmcnt(0)
	s_barrier
; #define PG8_STAGE(bufoff, gbase, voff) do { _Pragma("unroll") for (int _i = 0; _i < 2; ++_i) \
;         __builtin_amdgcn_global_load_lds((const unsigned*)((const char*)(gbase) + (voff)[_i]), (PG8_LAS unsigned*)(lds + (bufoff) + ldsw + _i * 8192), 16, 0, 0); } while (0)
; #define PG8_LDA(dst, b, h) do { _Pragma("unroll") for (int m = 0; m < 4; ++m) _Pragma("unroll") for (int k = 0; k < 2; ++k) dst[m][k] = *(const PG8_LAS bf16x8*)(lds + PG8_SA(b, h) + aoff + m * 2048 + k * 1024); } while (0)
; #define PG8_LDB(dst, b, h) do { _Pragma("unroll") for (int n = 0; n < 2; ++n) _Pragma("unroll") for (int k = 0; k < 2; ++k) dst[n][k] = *(const PG8_LAS bf16x8*)(lds + PG8_SB(b, h) + boff + n * 2048 + k * 1024); } while (0)
; #define PG8_MMA(ai, bj, At, Bt) do { __builtin_amdgcn_s_setprio(1); _Pragma("unroll") for (int m = 0; m < 4; ++m) _Pragma("unroll") for (int n = 0; n < 2; ++n) _Pragma("unroll") for (int k = 0; k < 2; ++k) \
;         acc[ai][bj][m][n] = __builtin_amdgcn_mfma_f32_16x16x32_bf16(Bt[n][k], At[m][k], acc[ai][bj][m][n], 0, 0, 0); __builtin_amdgcn_s_setprio(0); } while (0)
; #define PG8_WAIT_V(n) asm volatile("s_waitcnt vmcnt(" #n ")" ::: "memory")
; #define PG8_WAIT_L(n) asm volatile("s_waitcnt lgkmcnt(" #n ")" ::: "memory")
; #define PG8_BAR __builtin_amdgcn_s_barrier()
; #define PG8_SCHED __builtin_amdgcn_sched_barrier(0)
; template <class Epi, class Sched, bool ALIGN_EPI = false, bool SP2 = false>
; __device__ __forceinline__ void gemm_phase(PG8_LAS unsigned char* lds, const Gemm g, const Sched& S, const Epi& E) {
;     ...
;             PG8_WAIT_V(8); PG8_WAIT_L(0); PG8_BAR; PG8_MMA(1, 0, At, B0); PG8_MMA(1, 1, At, B1); PG8_BAR; PG8_SCHED;
;             PG8_LDB(B0, 1, 0); PG8_LDB(B1, 1, 1); PG8_SCHED; PG8_LDA(At, 1, 0); PG8_STAGE(PG8_SA(0, 1), a2 + hstep, voffA);
;             PG8_WAIT_V(8); PG8_WAIT_L(0); PG8_BAR; PG8_MMA(0, 0, At, B0); PG8_MMA(0, 1, At, B1); PG8_BAR; PG8_SCHED;
	s_setprio 1
	s_waitcnt lgkmcnt(0)
	v_mfma_f32_16x16x32_bf16 v[62:65], v[148:151], v[180:183], v[62:65]
	v_mfma_f32_16x16x32_bf16 v[62:65], v[152:155], v[184:187], v[62:65]
	v_mfma_f32_16x16x32_bf16 v[58:61], v[156:159], v[180:183], v[58:61]
	v_mfma_f32_16x16x32_bf16 v[58:61], v[160:163], v[184:187], v[58:61]
	v_mfma_f32_16x16x32_bf16 v[46:49], v[148:151], v[188:191], v[46:49]
	v_mfma_f32_16x16x32_bf16 v[46:49], v[152:155], v[192:195], v[46:49]
	v_mfma_f32_16x16x32_bf16 v[42:45], v[156:159], v[188:191], v[42:45]
	v_mfma_f32_16x16x32_bf16 v[42:45], v[160:163], v[192:195], v[42:45]
	v_mfma_f32_16x16x32_bf16 v[30:33], v[148:151], v[196:199], v[30:33]
	v_mfma_f32_16x16x32_bf16 v[30:33], v[152:155], v[220:223], v[30:33]
	v_mfma_f32_16x16x32_bf16 v[26:29], v[156:159], v[196:199], v[26:29]
	v_mfma_f32_16x16x32_bf16 v[26:29], v[160:163], v[220:223], v[26:29]
	v_mfma_f32_16x16x32_bf16 v[14:17], v[148:151], v[224:227], v[14:17]
	v_mfma_f32_16x16x32_bf16 v[14:17], v[152:155], v[228:231], v[14:17]
	v_mfma_f32_16x16x32_bf16 v[10:13], v[156:159], v[224:227], v[10:13]
	v_mfma_f32_16x16x32_bf16 v[10:13], v[160:163], v[228:231], v[10:13]
	s_setprio 0
	s_setprio 1
	v_mfma_f32_16x16x32_bf16 v[54:57], v[164:167], v[180:183], v[54:57]
	v_mfma_f32_16x16x32_bf16 v[54:57], v[168:171], v[184:187], v[54:57]
	v_mfma_f32_16x16x32_bf16 v[50:53], v[172:175], v[180:183], v[50:53]
	v_mfma_f32_16x16x32_bf16 v[50:53], v[176:179], v[184:187], v[50:53]
	v_mfma_f32_16x16x32_bf16 v[38:41], v[164:167], v[188:191], v[38:41]
	v_mfma_f32_16x16x32_bf16 v[38:41], v[168:171], v[192:195], v[38:41]
	v_mfma_f32_16x16x32_bf16 v[34:37], v[172:175], v[188:191], v[34:37]
	v_mfma_f32_16x16x32_bf16 v[34:37], v[176:179], v[192:195], v[34:37]
	v_mfma_f32_16x16x32_bf16 v[22:25], v[164:167], v[196:199], v[22:25]
	v_mfma_f32_16x16x32_bf16 v[22:25], v[168:171], v[220:223], v[22:25]
	v_mfma_f32_16x16x32_bf16 v[18:21], v[172:175], v[196:199], v[18:21]
	v_mfma_f32_16x16x32_bf16 v[18:21], v[176:179], v[220:223], v[18:21]
	v_mfma_f32_16x16x32_bf16 v[6:9], v[164:167], v[224:227], v[6:9]
	v_mfma_f32_16x16x32_bf16 v[6:9], v[168:171], v[228:231], v[6:9]
	v_mfma_f32_16x16x32_bf16 v[2:5], v[172:175], v[224:227], v[2:5]
	v_mfma_f32_16x16x32_bf16 v[2:5], v[176:179], v[228:231], v[2:5]
	s_setprio 0
	s_barrier
	s_add_i32 s12, 0, 0x18000
	s_add_i32 s13, 0, 0x1c000
	v_add_u32_e32 v160, s12, v216
	v_add_u32_e32 v176, s13, v216
	ds_read_b128 v[148:151], v160
	ds_read_b128 v[152:155], v160 offset:1024
	ds_read_b128 v[156:159], v160 offset:2048
	ds_read_b128 v[160:163], v160 offset:3072
	ds_read_b128 v[164:167], v176
	ds_read_b128 v[168:171], v176 offset:1024
	ds_read_b128 v[172:175], v176 offset:2048
	ds_read_b128 v[176:179], v176 offset:3072
	s_add_u32 s10, s26, 0x200000
	s_addc_u32 s11, s27, 0
	s_mov_b32 m0, s66
	v_lshl_add_u64 v[238:239], s[10:11], 0, v[0:1]
	ds_read_b128 v[180:183], v218 offset:32768
	ds_read_b128 v[184:187], v218 offset:33792
	ds_read_b128 v[188:191], v218 offset:34816
	ds_read_b128 v[192:195], v218 offset:35840
	ds_read_b128 v[196:199], v218 offset:36864
	ds_read_b128 v[220:223], v218 offset:37888
	ds_read_b128 v[224:227], v218 offset:38912
	ds_read_b128 v[228:231], v218 offset:39936
	global_load_lds_dwordx4 v[238:239], off
	v_lshl_add_u64 v[238:239], s[10:11], 0, v[142:143]
	s_mov_b32 m0, s67
	s_nop 0
	global_load_lds_dwordx4 v[238:239], off
	s_waitcnt vmcnt(8)
	s_waitcnt lgkmcnt(0)
	s_barrier
	s_setprio 1
	s_waitcnt lgkmcnt(0)
	v_mfma_f32_16x16x32_bf16 v[126:129], v[148:151], v[180:183], v[126:129]
	v_mfma_f32_16x16x32_bf16 v[126:129], v[152:155], v[184:187], v[126:129]
	v_mfma_f32_16x16x32_bf16 v[122:125], v[156:159], v[180:183], v[122:125]
	v_mfma_f32_16x16x32_bf16 v[122:125], v[160:163], v[184:187], v[122:125]
	v_mfma_f32_16x16x32_bf16 v[110:113], v[148:151], v[188:191], v[110:113]
	v_mfma_f32_16x16x32_bf16 v[110:113], v[152:155], v[192:195], v[110:113]
	v_mfma_f32_16x16x32_bf16 v[106:109], v[156:159], v[188:191], v[106:109]
	v_mfma_f32_16x16x32_bf16 v[106:109], v[160:163], v[192:195], v[106:109]
	v_mfma_f32_16x16x32_bf16 v[94:97], v[148:151], v[196:199], v[94:97]
	v_mfma_f32_16x16x32_bf16 v[94:97], v[152:155], v[220:223], v[94:97]
	v_mfma_f32_16x16x32_bf16 v[90:93], v[156:159], v[196:199], v[90:93]
	v_mfma_f32_16x16x32_bf16 v[90:93], v[160:163], v[220:223], v[90:93]
	v_mfma_f32_16x16x32_bf16 v[78:81], v[148:151], v[224:227], v[78:81]
	v_mfma_f32_16x16x32_bf16 v[78:81], v[152:155], v[228:231], v[78:81]
	v_mfma_f32_16x16x32_bf16 v[74:77], v[156:159], v[224:227], v[74:77]
	v_mfma_f32_16x16x32_bf16 v[74:77], v[160:163], v[228:231], v[74:77]
	s_setprio 0
	s_setprio 1
	v_mfma_f32_16x16x32_bf16 v[118:121], v[164:167], v[180:183], v[118:121]
	v_mfma_f32_16x16x32_bf16 v[118:121], v[168:171], v[184:187], v[118:121]
	v_mfma_f32_16x16x32_bf16 v[114:117], v[172:175], v[180:183], v[114:117]
	v_mfma_f32_16x16x32_bf16 v[114:117], v[176:179], v[184:187], v[114:117]
	v_mfma_f32_16x16x32_bf16 v[102:105], v[164:167], v[188:191], v[102:105]
	v_mfma_f32_16x16x32_bf16 v[102:105], v[168:171], v[192:195], v[102:105]
	v_mfma_f32_16x16x32_bf16 v[98:101], v[172:175], v[188:191], v[98:101]
	v_mfma_f32_16x16x32_bf16 v[98:101], v[176:179], v[192:195], v[98:101]
	v_mfma_f32_16x16x32_bf16 v[86:89], v[164:167], v[196:199], v[86:89]
	v_mfma_f32_16x16x32_bf16 v[86:89], v[168:171], v[220:223], v[86:89]
	v_mfma_f32_16x16x32_bf16 v[82:85], v[172:175], v[196:199], v[82:85]
	v_mfma_f32_16x16x32_bf16 v[82:85], v[176:179], v[220:223], v[82:85]
	v_mfma_f32_16x16x32_bf16 v[70:73], v[164:167], v[224:227], v[70:73]
	v_mfma_f32_16x16x32_bf16 v[70:73], v[168:171], v[228:231], v[70:73]
	v_mfma_f32_16x16x32_bf16 v[66:69], v[172:175], v[224:227], v[66:69]
	v_mfma_f32_16x16x32_bf16 v[66:69], v[176:179], v[228:231], v[66:69]
	s_setprio 0
	s_barrier
; __device__ __forceinline__ unsigned cvt_pk_bf16(float lo, float hi) { unsigned r; asm volatile("v_cvt_pk_bf16_f32 %0, %1, %2" : "=v"(r) : "v"(lo), "v"(hi)); return r; }
; #define PG8_WAIT_V(n) asm volatile("s_waitcnt vmcnt(" #n ")" ::: "memory")
; #define PG8_BAR __builtin_amdgcn_s_barrier()
;     __device__ __forceinline__ void operator()(const f32x4 (&acc)[2][2][4][2], const Unit& u, int wr, int wc, int fr, int fq) const {
;         const int row0 = u.pm * BM + wr * 64 + fr; const int col0 = u.pn * BM + wc * 32 + 4 * fq;
; #pragma unroll
;         for (int ai = 0; ai < 2; ++ai) {
;             u32x2 bv[4][2][2];
; #pragma unroll
;             for (int m = 0; m < 4; ++m) { const size_t off = (size_t)(row0 + ai * HALF + m * 16) * ldc + col0;
; #pragma unroll
;                 for (int bj = 0; bj < 2; ++bj)
; #pragma unroll
;                     for (int n = 0; n < 2; ++n) bv[m][bj][n] = *(const u32x2*)(xb + off + bj * HALF + n * 16); }
;             asm volatile("" ::: "memory");
; #pragma unroll
;             for (int m = 0; m < 4; ++m) {
;                 const int row = row0 + ai * HALF + m * 16;
;                 const size_t off = (size_t)row * ldc + col0;
;                 float s = 0.f;
; #pragma unroll
;                 for (int bj = 0; bj < 2; ++bj)
; #pragma unroll
;                     for (int n = 0; n < 2; ++n) {
;                         const size_t c = off + bj * HALF + n * 16;
;                         const u32x2 w0 = bv[m][bj][n];
;                         const f32x4 b = {__uint_as_float(w0.x << 16), __uint_as_float(w0.x & 0xffff0000u), __uint_as_float(w0.y << 16), __uint_as_float(w0.y & 0xffff0000u)};
;                         const f32x4 o = b + acc[ai][bj][m][n];
;                         if (fin) { *(f32x4*)(outf + c) = o; }
;                         else { u32x2 w; w.x = cvt_pk_bf16(o[0], o[1]); w.y = cvt_pk_bf16(o[2], o[3]); *(u32x2*)(xb + c) = w;
; template <class Epi, class Sched, bool ALIGN_EPI = false, bool SP2 = false>
; __device__ __forceinline__ void gemm_phase(PG8_LAS unsigned char* lds, const Gemm g, const Sched& S, const Epi& E) {
;     ...
;             PG8_LDA(At, 1, 1); PG8_STAGE(PG8_SB(1, 0), b3, voffB); PG8_STAGE(PG8_SB(1, 1), b3 + hstep, voffB); PG8_STAGE(PG8_SA(1, 0), a3, voffA);
;             PG8_WAIT_V(8); PG8_WAIT_L(0); PG8_BAR; PG8_MMA(1, 0, At, B0); PG8_MMA(1, 1, At, B1); PG8_BAR; PG8_SCHED;
	s_add_i32 s10, s12, s63
	v_lshl_add_u64 v[200:201], v[200:201], 0, s[30:31]
	s_mov_b32 m0, s10
	ds_read_b128 v[180:183], v218 offset:49152
	ds_read_b128 v[184:187], v218 offset:50176
	ds_read_b128 v[188:191], v218 offset:51200
	ds_read_b128 v[192:195], v218 offset:52224
	ds_read_b128 v[196:199], v218 offset:53248
	ds_read_b128 v[220:223], v218 offset:54272
	ds_read_b128 v[224:227], v218 offset:55296
	ds_read_b128 v[228:231], v218 offset:56320
	global_load_lds_dwordx4 v[200:201], off
	s_add_i32 m0, s10, 0x2000
	s_add_u32 s10, s24, 0x200080
	v_lshl_add_u64 v[200:201], v[232:233], 0, s[30:31]
	s_addc_u32 s11, s25, 0
	s_add_i32 s12, s13, s63
	global_load_lds_dwordx4 v[200:201], off
	v_lshl_add_u64 v[200:201], s[10:11], 0, v[0:1]
	s_mov_b32 m0, s12
	s_nop 0
	global_load_lds_dwordx4 v[200:201], off
	v_lshl_add_u64 v[200:201], s[10:11], 0, v[142:143]
	s_add_i32 m0, s12, 0x2000
	s_nop 0
	global_load_lds_dwordx4 v[200:201], off
	v_lshl_add_u64 v[200:201], v[234:235], 0, s[30:31]
	s_mov_b32 m0, s68
	s_nop 0
	global_load_lds_dwordx4 v[200:201], off
	v_lshl_add_u64 v[200:201], v[236:237], 0, s[30:31]
	s_mov_b32 m0, s69
	s_nop 0
	global_load_lds_dwordx4 v[200:201], off
	s_waitcnt vmcnt(8)
	s_waitcnt lgkmcnt(0)
	s_barrier
	s_setprio 1
	s_waitcnt lgkmcnt(0)
	v_mfma_f32_16x16x32_bf16 v[62:65], v[148:151], v[180:183], v[62:65]
	v_mfma_f32_16x16x32_bf16 v[62:65], v[152:155], v[184:187], v[62:65]
	v_mfma_f32_16x16x32_bf16 v[58:61], v[156:159], v[180:183], v[58:61]
	v_mfma_f32_16x16x32_bf16 v[58:61], v[160:163], v[184:187], v[58:61]
	v_mfma_f32_16x16x32_bf16 v[46:49], v[148:151], v[188:191], v[46:49]
	v_mfma_f32_16x16x32_bf16 v[46:49], v[152:155], v[192:195], v[46:49]
	v_mfma_f32_16x16x32_bf16 v[42:45], v[156:159], v[188:191], v[42:45]
	v_mfma_f32_16x16x32_bf16 v[42:45], v[160:163], v[192:195], v[42:45]
	v_mfma_f32_16x16x32_bf16 v[30:33], v[148:151], v[196:199], v[30:33]
	v_mfma_f32_16x16x32_bf16 v[30:33], v[152:155], v[220:223], v[30:33]
	v_mfma_f32_16x16x32_bf16 v[26:29], v[156:159], v[196:199], v[26:29]
	v_mfma_f32_16x16x32_bf16 v[26:29], v[160:163], v[220:223], v[26:29]
	v_mfma_f32_16x16x32_bf16 v[14:17], v[148:151], v[224:227], v[14:17]
	v_mfma_f32_16x16x32_bf16 v[14:17], v[152:155], v[228:231], v[14:17]
	v_mfma_f32_16x16x32_bf16 v[10:13], v[156:159], v[224:227], v[10:13]
	v_mfma_f32_16x16x32_bf16 v[10:13], v[160:163], v[228:231], v[10:13]
	s_setprio 0
	s_setprio 1
	v_mfma_f32_16x16x32_bf16 v[54:57], v[164:167], v[180:183], v[54:57]
	v_mfma_f32_16x16x32_bf16 v[54:57], v[168:171], v[184:187], v[54:57]
	v_mfma_f32_16x16x32_bf16 v[50:53], v[172:175], v[180:183], v[50:53]
	v_mfma_f32_16x16x32_bf16 v[50:53], v[176:179], v[184:187], v[50:53]
	v_mfma_f32_16x16x32_bf16 v[38:41], v[164:167], v[188:191], v[38:41]
	v_mfma_f32_16x16x32_bf16 v[38:41], v[168:171], v[192:195], v[38:41]
	v_mfma_f32_16x16x32_bf16 v[34:37], v[172:175], v[188:191], v[34:37]
	v_mfma_f32_16x16x32_bf16 v[34:37], v[176:179], v[192:195], v[34:37]
	v_mfma_f32_16x16x32_bf16 v[22:25], v[164:167], v[196:199], v[22:25]
	v_mfma_f32_16x16x32_bf16 v[22:25], v[168:171], v[220:223], v[22:25]
	v_mfma_f32_16x16x32_bf16 v[18:21], v[172:175], v[196:199], v[18:21]
	v_mfma_f32_16x16x32_bf16 v[18:21], v[176:179], v[220:223], v[18:21]
	v_mfma_f32_16x16x32_bf16 v[6:9], v[164:167], v[224:227], v[6:9]
	v_mfma_f32_16x16x32_bf16 v[6:9], v[168:171], v[228:231], v[6:9]
	v_mfma_f32_16x16x32_bf16 v[2:5], v[172:175], v[224:227], v[2:5]
	v_mfma_f32_16x16x32_bf16 v[2:5], v[176:179], v[228:231], v[2:5]
	s_setprio 0
	s_barrier
	s_add_i32 s22, s22, 2
	s_add_u32 s14, s14, 0x100
	s_addc_u32 s15, s15, 0
	s_cmpk_gt_u32 s22, 0x7d
	s_mov_b64 s[16:17], s[18:19]
	s_cbranch_scc0 .LBB0_758
	v_lshl_add_u32 v152, s4, 8, v215
	v_lshl_or_b32 v148, s2, 8, v217
	v_ashrrev_i32_e32 v149, 31, v148
	v_ashrrev_i32_e32 v153, 31, v152
	v_or_b32_e32 v176, 16, v152
	v_lshl_add_u64 v[150:151], v[148:149], 1, s[50:51]
	v_lshlrev_b64 v[154:155], 12, v[152:153]
	v_ashrrev_i32_e32 v177, 31, v176
	v_or_b32_e32 v164, 32, v152
	v_lshl_add_u64 v[198:199], v[150:151], 0, v[154:155]
	v_lshlrev_b64 v[154:155], 12, v[176:177]
	v_ashrrev_i32_e32 v165, 31, v164
	v_lshl_add_u64 v[186:187], v[150:151], 0, v[154:155]
	v_lshlrev_b64 v[154:155], 12, v[164:165]
	v_lshl_add_u64 v[174:175], v[150:151], 0, v[154:155]
	v_or_b32_e32 v154, 48, v152
	v_ashrrev_i32_e32 v155, 31, v154
	v_lshlrev_b64 v[156:157], 12, v[154:155]
	v_lshl_add_u64 v[162:163], v[150:151], 0, v[156:157]
	global_load_dwordx2 v[192:193], v[198:199], off
	global_load_dwordx2 v[196:197], v[198:199], off offset:32
	global_load_dwordx2 v[194:195], v[198:199], off offset:256
	global_load_dwordx2 v[190:191], v[198:199], off offset:288
	global_load_dwordx2 v[188:189], v[186:187], off
	global_load_dwordx2 v[184:185], v[186:187], off offset:32
	global_load_dwordx2 v[182:183], v[186:187], off offset:256
	global_load_dwordx2 v[180:181], v[186:187], off offset:288
	global_load_dwordx2 v[178:179], v[174:175], off
	global_load_dwordx2 v[172:173], v[174:175], off offset:32
	global_load_dwordx2 v[170:171], v[174:175], off offset:256
	global_load_dwordx2 v[168:169], v[174:175], off offset:288
	global_load_dwordx2 v[166:167], v[162:163], off
	global_load_dwordx2 v[160:161], v[162:163], off offset:32
	global_load_dwordx2 v[158:159], v[162:163], off offset:256
	global_load_dwordx2 v[156:157], v[162:163], off offset:288
	v_readlane_b32 s4, v244, 52
	v_readlane_b32 s5, v244, 53
	s_mov_b64 s[16:17], -1
	s_andn2_b64 vcc, exec, s[4:5]
	v_cndmask_b32_e64 v200, 0, 1, s[4:5]
	v_cmp_ne_u32_e64 s[44:45], 1, v200
	v_lshlrev_b64 v[200:201], 11, v[152:153]
	v_lshl_add_u64 v[200:201], v[200:201], 0, v[148:149]
	s_waitcnt vmcnt(0)
	v_lshlrev_b32_e32 v220, 16, v192
	v_and_b32_e32 v221, 0xffff0000, v192
	v_lshlrev_b32_e32 v192, 16, v193
	v_and_b32_e32 v193, 0xffff0000, v193
	v_pk_add_f32 v[128:129], v[128:129], v[192:193]
	v_pk_add_f32 v[126:127], v[126:127], v[220:221]
	v_lshl_add_u64 v[192:193], v[200:201], 2, s[48:49]
	s_cbranch_vccnz .LBB0_761
	s_mov_b64 s[16:17], 0
	global_store_dwordx4 v[192:193], v[126:129], off
